# ssd_y_unit hand-scheduled: 4-stage software pipeline with loads issued one stage ahead (was one dependent load at a time)
# speedup vs baseline: 1.0085x; 1.0085x over previous
;     DEVI bf16_t* proj() const { return (bf16_t*)(ws + WS_PROJ); }
;     DEVI bf16_t* prevb() const { return (bf16_t*)(ws + WS_XBC); }
;     DEVI float* acum() const { return (float*)(ws + WS_ACUM); }
;     DEVI bf16_t* cact() const { return (bf16_t*)(ws + WS_CB); }
;     DEVI float* ydg() const { return (float*)(ws + WS_YZ); }
; #define LAS __attribute__((address_space(3)))
; DEVI float silu_fast(float x) { return x / (1.f + __expf(-x)); }
; DEVI void ssd_y_unit(const P& p, int l, int ci, LAS unsigned char* lds, int tid, int wave, int lane) {
;     const int c32 = lane & 31, hh = lane >> 5, r0 = ci * 64, g = wave >> 2;
;     LAS float* part = (LAS float*)lds;
;     const f32x16_t z16 = {0.f, 0.f, 0.f, 0.f, 0.f, 0.f, 0.f, 0.f, 0.f, 0.f, 0.f, 0.f, 0.f, 0.f, 0.f, 0.f};
;     float y[2][2][16];
; #pragma unroll
;     for (int tb = 0; tb < 2; ++tb) {
;         const size_t r = (size_t)r0 + 32 * tb + c32; const float eat = __expf(p.acum()[r * 8 + wave]); float ssq = 0.f;
; #pragma unroll
;         for (int pb = 0; pb < 2; ++pb) {
;             f32x16_t YO = z16;
; #pragma unroll
;             for (int kk = 0; kk < 4; ++kk) {
;                 const bf16x8_t a = *(const bf16x8_t*)(p.prevb() + ((size_t)(ci * 8 + wave) * 64 + 32 * pb + c32) * 64 + 16 * kk + 8 * hh);
;                 const bf16x8_t b = *(const bf16x8_t*)(p.cact() + r * 128 + g * 64 + 16 * kk + 8 * hh);
;                 YO = __builtin_amdgcn_mfma_f32_32x32x16_bf16(a, b, YO, 0, 0, 0);
;             }
; #pragma unroll
;             for (int q = 0; q < 4; ++q) { const int p0 = wave * 64 + 32 * pb + 8 * q + 4 * hh;
;                 const float4 yd = *(const float4*)(p.ydg() + r * 512 + p0); const uint2 zz = *(const uint2*)(p.proj() + r * NP + O_Z + p0);
;                 const float z0 = __uint_as_float(zz.x << 16), z1 = __uint_as_float(zz.x & 0xffff0000u), z2 = __uint_as_float(zz.y << 16), z3 = __uint_as_float(zz.y & 0xffff0000u);
;                 const float v0 = (yd.x + YO[4 * q] * eat) * silu_fast(z0), v1 = (yd.y + YO[4 * q + 1] * eat) * silu_fast(z1), v2 = (yd.z + YO[4 * q + 2] * eat) * silu_fast(z2), v3 = (yd.w + YO[4 * q + 3] * eat) * silu_fast(z3);
;                 y[tb][pb][4 * q] = v0; y[tb][pb][4 * q + 1] = v1; y[tb][pb][4 * q + 2] = v2; y[tb][pb][4 * q + 3] = v3; ssq += v0 * v0 + v1 * v1 + v2 * v2 + v3 * v3; }
.LBB0_700:
	s_load_dwordx2 s[8:9], s[0:1], 0x98
	s_waitcnt lgkmcnt(0)
	v_lshl_add_u64 v[226:227], s[8:9], 0, v[62:63]
	v_lshl_add_u64 v[226:227], v[58:59], 2, v[226:227]
	s_ashr_i32 s7, s6, 31
	s_lshl_b64 s[8:9], s[6:7], 13
	v_lshl_add_u64 v[222:223], v[60:61], 0, s[8:9]
	s_nop 0
	v_add_co_u32_e32 v194, vcc, 0x1000, v222
	s_nop 1
	v_addc_co_u32_e32 v195, vcc, 0, v223, vcc
	v_mov_b32_e32 v233, 0
	v_or_b32_e32 v232, s11, v54
	v_lshlrev_b64 v[234:235], 5, v[232:233]
	v_lshl_add_u64 v[234:235], s[4:5], 0, v[234:235]
	v_lshlrev_b64 v[236:237], 8, v[232:233]
	v_lshl_add_u64 v[236:237], v[56:57], 0, v[236:237]
	v_lshlrev_b64 v[238:239], 11, v[232:233]
	v_lshl_add_u64 v[238:239], v[68:69], 0, v[238:239]
	v_mad_i64_i32 v[240:241], s[8:9], v232, s88, v[70:71]
	global_load_dword v216, v[234:235], off
	global_load_dwordx4 v[34:37], v[236:237], off offset:0
	global_load_dwordx4 v[38:41], v[236:237], off offset:32
	global_load_dwordx4 v[42:45], v[236:237], off offset:64
	global_load_dwordx4 v[46:49], v[236:237], off offset:96
	global_load_dwordx4 v[18:21], v[222:223], off offset:0
	global_load_dwordx4 v[22:25], v[222:223], off offset:32
	global_load_dwordx4 v[26:29], v[222:223], off offset:64
	global_load_dwordx4 v[30:33], v[222:223], off offset:96
	global_load_dwordx4 v[74:77], v[238:239], off offset:0
	global_load_dwordx4 v[78:81], v[238:239], off offset:32
	global_load_dwordx4 v[82:85], v[238:239], off offset:64
	global_load_dwordx4 v[86:89], v[238:239], off offset:96
	global_load_dwordx2 v[90:91], v[240:241], off offset:0
	global_load_dwordx2 v[92:93], v[240:241], off offset:16
	global_load_dwordx2 v[94:95], v[240:241], off offset:32
	global_load_dwordx2 v[96:97], v[240:241], off offset:48
	s_waitcnt vmcnt(16)
	v_mul_f32_e32 v216, 0x3fb8aa3b, v216
	v_exp_f32_e32 v216, v216
	v_mov_b32_e32 v217, 0
	s_waitcnt vmcnt(11)
	v_mfma_f32_32x32x16_bf16 v[2:17], v[18:21], v[34:37], 0
	s_waitcnt vmcnt(10)
	v_mfma_f32_32x32x16_bf16 v[2:17], v[22:25], v[38:41], v[2:17]
	s_waitcnt vmcnt(9)
	v_mfma_f32_32x32x16_bf16 v[2:17], v[26:29], v[42:45], v[2:17]
	s_waitcnt vmcnt(8)
	v_mfma_f32_32x32x16_bf16 v[2:17], v[30:33], v[46:49], v[2:17]
	s_nop 7
	global_load_dwordx4 v[18:21], v[194:195], off offset:0
	global_load_dwordx4 v[22:25], v[194:195], off offset:32
	global_load_dwordx4 v[26:29], v[194:195], off offset:64
	global_load_dwordx4 v[30:33], v[194:195], off offset:96
	global_load_dwordx4 v[98:101], v[238:239], off offset:128
	global_load_dwordx4 v[102:105], v[238:239], off offset:160
	global_load_dwordx4 v[106:109], v[238:239], off offset:192
	global_load_dwordx4 v[110:113], v[238:239], off offset:224
	global_load_dwordx2 v[114:115], v[240:241], off offset:64
	global_load_dwordx2 v[116:117], v[240:241], off offset:80
	global_load_dwordx2 v[118:119], v[240:241], off offset:96
	global_load_dwordx2 v[120:121], v[240:241], off offset:112
	s_nop 15
	s_waitcnt vmcnt(15)
	v_lshlrev_b32_e32 v218, 16, v90
	v_and_b32_e32 v219, 0xffff0000, v90
	v_lshlrev_b32_e32 v220, 16, v91
	v_and_b32_e32 v221, 0xffff0000, v91
	v_fma_f32 v124, v216, v2, v74
	v_mul_f32_e32 v50, 0xbfb8aa3b, v218
	v_exp_f32_e32 v50, v50
	s_nop 0
	v_add_f32_e32 v50, 1.0, v50
	v_div_scale_f32 v51, s[8:9], v50, v50, v218
	v_rcp_f32_e32 v52, v51
	s_nop 0
	v_fma_f32 v53, -v51, v52, 1.0
	v_fmac_f32_e32 v52, v53, v52
	v_div_scale_f32 v53, vcc, v218, v50, v218
	v_mul_f32_e32 v66, v53, v52
	v_fma_f32 v122, -v51, v66, v53
	v_fmac_f32_e32 v66, v122, v52
	v_fma_f32 v51, -v51, v66, v53
	v_div_fmas_f32 v51, v51, v52, v66
	v_div_fixup_f32 v123, v51, v50, v218
	v_mul_f32_e32 v125, v124, v123
	v_fmac_f32_e32 v217, v125, v125
	v_fma_f32 v124, v216, v3, v75
	v_mul_f32_e32 v50, 0xbfb8aa3b, v219
	v_exp_f32_e32 v50, v50
	s_nop 0
	v_add_f32_e32 v50, 1.0, v50
	v_div_scale_f32 v51, s[8:9], v50, v50, v219
	v_rcp_f32_e32 v52, v51
	s_nop 0
	v_fma_f32 v53, -v51, v52, 1.0
	v_fmac_f32_e32 v52, v53, v52
	v_div_scale_f32 v53, vcc, v219, v50, v219
	v_mul_f32_e32 v66, v53, v52
	v_fma_f32 v122, -v51, v66, v53
	v_fmac_f32_e32 v66, v122, v52
	v_fma_f32 v51, -v51, v66, v53
	v_div_fmas_f32 v51, v51, v52, v66
	v_div_fixup_f32 v123, v51, v50, v219
	v_mul_f32_e32 v126, v124, v123
	v_fmac_f32_e32 v217, v126, v126
	v_fma_f32 v124, v216, v4, v76
	v_mul_f32_e32 v50, 0xbfb8aa3b, v220
	v_exp_f32_e32 v50, v50
	s_nop 0
	v_add_f32_e32 v50, 1.0, v50
	v_div_scale_f32 v51, s[8:9], v50, v50, v220
	v_rcp_f32_e32 v52, v51
	s_nop 0
	v_fma_f32 v53, -v51, v52, 1.0
	v_fmac_f32_e32 v52, v53, v52
	v_div_scale_f32 v53, vcc, v220, v50, v220
	v_mul_f32_e32 v66, v53, v52
	v_fma_f32 v122, -v51, v66, v53
	v_fmac_f32_e32 v66, v122, v52
	v_fma_f32 v51, -v51, v66, v53
	v_div_fmas_f32 v51, v51, v52, v66
	v_div_fixup_f32 v123, v51, v50, v220
	v_mul_f32_e32 v127, v124, v123
	v_fmac_f32_e32 v217, v127, v127
	v_fma_f32 v124, v216, v5, v77
	v_mul_f32_e32 v50, 0xbfb8aa3b, v221
	v_exp_f32_e32 v50, v50
	s_nop 0
	v_add_f32_e32 v50, 1.0, v50
	v_div_scale_f32 v51, s[8:9], v50, v50, v221
	v_rcp_f32_e32 v52, v51
	s_nop 0
	v_fma_f32 v53, -v51, v52, 1.0
	v_fmac_f32_e32 v52, v53, v52
	v_div_scale_f32 v53, vcc, v221, v50, v221
	v_mul_f32_e32 v66, v53, v52
	v_fma_f32 v122, -v51, v66, v53
	v_fmac_f32_e32 v66, v122, v52
	v_fma_f32 v51, -v51, v66, v53
	v_div_fmas_f32 v51, v51, v52, v66
	v_div_fixup_f32 v123, v51, v50, v221
	v_mul_f32_e32 v128, v124, v123
	v_fmac_f32_e32 v217, v128, v128
	s_waitcnt vmcnt(14)
;     DEVI bf16_t* proj() const { return (bf16_t*)(ws + WS_PROJ); }
;     DEVI float* ydg() const { return (float*)(ws + WS_YZ); }
; DEVI float silu_fast(float x) { return x / (1.f + __expf(-x)); }
; DEVI void ssd_y_unit(const P& p, int l, int ci, LAS unsigned char* lds, int tid, int wave, int lane) {
;     ...
;             for (int q = 0; q < 4; ++q) { const int p0 = wave * 64 + 32 * pb + 8 * q + 4 * hh;
;                 const float4 yd = *(const float4*)(p.ydg() + r * 512 + p0); const uint2 zz = *(const uint2*)(p.proj() + r * NP + O_Z + p0);
;                 const float z0 = __uint_as_float(zz.x << 16), z1 = __uint_as_float(zz.x & 0xffff0000u), z2 = __uint_as_float(zz.y << 16), z3 = __uint_as_float(zz.y & 0xffff0000u);
;                 const float v0 = (yd.x + YO[4 * q] * eat) * silu_fast(z0), v1 = (yd.y + YO[4 * q + 1] * eat) * silu_fast(z1), v2 = (yd.z + YO[4 * q + 2] * eat) * silu_fast(z2), v3 = (yd.w + YO[4 * q + 3] * eat) * silu_fast(z3);
;                 y[tb][pb][4 * q] = v0; y[tb][pb][4 * q + 1] = v1; y[tb][pb][4 * q + 2] = v2; y[tb][pb][4 * q + 3] = v3; ssq += v0 * v0 + v1 * v1 + v2 * v2 + v3 * v3; }
	v_lshlrev_b32_e32 v218, 16, v92
	v_and_b32_e32 v219, 0xffff0000, v92
	v_lshlrev_b32_e32 v220, 16, v93
	v_and_b32_e32 v221, 0xffff0000, v93
	v_fma_f32 v124, v216, v6, v78
	v_mul_f32_e32 v50, 0xbfb8aa3b, v218
	v_exp_f32_e32 v50, v50
	s_nop 0
	v_add_f32_e32 v50, 1.0, v50
	v_div_scale_f32 v51, s[8:9], v50, v50, v218
	v_rcp_f32_e32 v52, v51
	s_nop 0
	v_fma_f32 v53, -v51, v52, 1.0
	v_fmac_f32_e32 v52, v53, v52
	v_div_scale_f32 v53, vcc, v218, v50, v218
	v_mul_f32_e32 v66, v53, v52
	v_fma_f32 v122, -v51, v66, v53
	v_fmac_f32_e32 v66, v122, v52
	v_fma_f32 v51, -v51, v66, v53
	v_div_fmas_f32 v51, v51, v52, v66
	v_div_fixup_f32 v123, v51, v50, v218
	v_mul_f32_e32 v129, v124, v123
	v_fmac_f32_e32 v217, v129, v129
	v_fma_f32 v124, v216, v7, v79
	v_mul_f32_e32 v50, 0xbfb8aa3b, v219
	v_exp_f32_e32 v50, v50
	s_nop 0
	v_add_f32_e32 v50, 1.0, v50
	v_div_scale_f32 v51, s[8:9], v50, v50, v219
	v_rcp_f32_e32 v52, v51
	s_nop 0
	v_fma_f32 v53, -v51, v52, 1.0
	v_fmac_f32_e32 v52, v53, v52
	v_div_scale_f32 v53, vcc, v219, v50, v219
	v_mul_f32_e32 v66, v53, v52
	v_fma_f32 v122, -v51, v66, v53
	v_fmac_f32_e32 v66, v122, v52
	v_fma_f32 v51, -v51, v66, v53
	v_div_fmas_f32 v51, v51, v52, v66
	v_div_fixup_f32 v123, v51, v50, v219
	v_mul_f32_e32 v130, v124, v123
	v_fmac_f32_e32 v217, v130, v130
	v_fma_f32 v124, v216, v8, v80
	v_mul_f32_e32 v50, 0xbfb8aa3b, v220
	v_exp_f32_e32 v50, v50
	s_nop 0
	v_add_f32_e32 v50, 1.0, v50
	v_div_scale_f32 v51, s[8:9], v50, v50, v220
	v_rcp_f32_e32 v52, v51
	s_nop 0
	v_fma_f32 v53, -v51, v52, 1.0
	v_fmac_f32_e32 v52, v53, v52
	v_div_scale_f32 v53, vcc, v220, v50, v220
	v_mul_f32_e32 v66, v53, v52
	v_fma_f32 v122, -v51, v66, v53
	v_fmac_f32_e32 v66, v122, v52
	v_fma_f32 v51, -v51, v66, v53
	v_div_fmas_f32 v51, v51, v52, v66
	v_div_fixup_f32 v123, v51, v50, v220
	v_mul_f32_e32 v131, v124, v123
	v_fmac_f32_e32 v217, v131, v131
	v_fma_f32 v124, v216, v9, v81
	v_mul_f32_e32 v50, 0xbfb8aa3b, v221
	v_exp_f32_e32 v50, v50
	s_nop 0
	v_add_f32_e32 v50, 1.0, v50
	v_div_scale_f32 v51, s[8:9], v50, v50, v221
	v_rcp_f32_e32 v52, v51
	s_nop 0
	v_fma_f32 v53, -v51, v52, 1.0
	v_fmac_f32_e32 v52, v53, v52
	v_div_scale_f32 v53, vcc, v221, v50, v221
	v_mul_f32_e32 v66, v53, v52
	v_fma_f32 v122, -v51, v66, v53
	v_fmac_f32_e32 v66, v122, v52
	v_fma_f32 v51, -v51, v66, v53
	v_div_fmas_f32 v51, v51, v52, v66
	v_div_fixup_f32 v123, v51, v50, v221
	v_mul_f32_e32 v132, v124, v123
	v_fmac_f32_e32 v217, v132, v132
	s_waitcnt vmcnt(13)
	v_lshlrev_b32_e32 v218, 16, v94
	v_and_b32_e32 v219, 0xffff0000, v94
	v_lshlrev_b32_e32 v220, 16, v95
	v_and_b32_e32 v221, 0xffff0000, v95
	v_fma_f32 v124, v216, v10, v82
	v_mul_f32_e32 v50, 0xbfb8aa3b, v218
	v_exp_f32_e32 v50, v50
	s_nop 0
	v_add_f32_e32 v50, 1.0, v50
	v_div_scale_f32 v51, s[8:9], v50, v50, v218
	v_rcp_f32_e32 v52, v51
	s_nop 0
	v_fma_f32 v53, -v51, v52, 1.0
	v_fmac_f32_e32 v52, v53, v52
	v_div_scale_f32 v53, vcc, v218, v50, v218
	v_mul_f32_e32 v66, v53, v52
	v_fma_f32 v122, -v51, v66, v53
	v_fmac_f32_e32 v66, v122, v52
	v_fma_f32 v51, -v51, v66, v53
	v_div_fmas_f32 v51, v51, v52, v66
	v_div_fixup_f32 v123, v51, v50, v218
	v_mul_f32_e32 v133, v124, v123
	v_fmac_f32_e32 v217, v133, v133
	v_fma_f32 v124, v216, v11, v83
	v_mul_f32_e32 v50, 0xbfb8aa3b, v219
	v_exp_f32_e32 v50, v50
	s_nop 0
	v_add_f32_e32 v50, 1.0, v50
	v_div_scale_f32 v51, s[8:9], v50, v50, v219
	v_rcp_f32_e32 v52, v51
	s_nop 0
	v_fma_f32 v53, -v51, v52, 1.0
	v_fmac_f32_e32 v52, v53, v52
	v_div_scale_f32 v53, vcc, v219, v50, v219
	v_mul_f32_e32 v66, v53, v52
	v_fma_f32 v122, -v51, v66, v53
	v_fmac_f32_e32 v66, v122, v52
	v_fma_f32 v51, -v51, v66, v53
	v_div_fmas_f32 v51, v51, v52, v66
	v_div_fixup_f32 v123, v51, v50, v219
	v_mul_f32_e32 v134, v124, v123
	v_fmac_f32_e32 v217, v134, v134
	v_fma_f32 v124, v216, v12, v84
	v_mul_f32_e32 v50, 0xbfb8aa3b, v220
	v_exp_f32_e32 v50, v50
	s_nop 0
	v_add_f32_e32 v50, 1.0, v50
	v_div_scale_f32 v51, s[8:9], v50, v50, v220
	v_rcp_f32_e32 v52, v51
	s_nop 0
	v_fma_f32 v53, -v51, v52, 1.0
	v_fmac_f32_e32 v52, v53, v52
	v_div_scale_f32 v53, vcc, v220, v50, v220
	v_mul_f32_e32 v66, v53, v52
	v_fma_f32 v122, -v51, v66, v53
	v_fmac_f32_e32 v66, v122, v52
	v_fma_f32 v51, -v51, v66, v53
	v_div_fmas_f32 v51, v51, v52, v66
	v_div_fixup_f32 v123, v51, v50, v220
	v_mul_f32_e32 v135, v124, v123
	v_fmac_f32_e32 v217, v135, v135
	v_fma_f32 v124, v216, v13, v85
	v_mul_f32_e32 v50, 0xbfb8aa3b, v221
	v_exp_f32_e32 v50, v50
	s_nop 0
	v_add_f32_e32 v50, 1.0, v50
	v_div_scale_f32 v51, s[8:9], v50, v50, v221
	v_rcp_f32_e32 v52, v51
	s_nop 0
	v_fma_f32 v53, -v51, v52, 1.0
	v_fmac_f32_e32 v52, v53, v52
	v_div_scale_f32 v53, vcc, v221, v50, v221
	v_mul_f32_e32 v66, v53, v52
	v_fma_f32 v122, -v51, v66, v53
	v_fmac_f32_e32 v66, v122, v52
	v_fma_f32 v51, -v51, v66, v53
	v_div_fmas_f32 v51, v51, v52, v66
	v_div_fixup_f32 v123, v51, v50, v221
	v_mul_f32_e32 v136, v124, v123
	v_fmac_f32_e32 v217, v136, v136
	s_waitcnt vmcnt(12)
;     DEVI bf16_t* proj() const { return (bf16_t*)(ws + WS_PROJ); }
;     DEVI bf16_t* prevb() const { return (bf16_t*)(ws + WS_XBC); }
;     DEVI bf16_t* cact() const { return (bf16_t*)(ws + WS_CB); }
;     DEVI float* ydg() const { return (float*)(ws + WS_YZ); }
; DEVI float silu_fast(float x) { return x / (1.f + __expf(-x)); }
; DEVI void ssd_y_unit(const P& p, int l, int ci, LAS unsigned char* lds, int tid, int wave, int lane) {
;     ...
;             f32x16_t YO = z16;
; #pragma unroll
;             for (int kk = 0; kk < 4; ++kk) {
;                 const bf16x8_t a = *(const bf16x8_t*)(p.prevb() + ((size_t)(ci * 8 + wave) * 64 + 32 * pb + c32) * 64 + 16 * kk + 8 * hh);
;                 const bf16x8_t b = *(const bf16x8_t*)(p.cact() + r * 128 + g * 64 + 16 * kk + 8 * hh);
;                 YO = __builtin_amdgcn_mfma_f32_32x32x16_bf16(a, b, YO, 0, 0, 0);
;             }
; #pragma unroll
;             for (int q = 0; q < 4; ++q) { const int p0 = wave * 64 + 32 * pb + 8 * q + 4 * hh;
;                 const float4 yd = *(const float4*)(p.ydg() + r * 512 + p0); const uint2 zz = *(const uint2*)(p.proj() + r * NP + O_Z + p0);
;                 const float z0 = __uint_as_float(zz.x << 16), z1 = __uint_as_float(zz.x & 0xffff0000u), z2 = __uint_as_float(zz.y << 16), z3 = __uint_as_float(zz.y & 0xffff0000u);
;                 const float v0 = (yd.x + YO[4 * q] * eat) * silu_fast(z0), v1 = (yd.y + YO[4 * q + 1] * eat) * silu_fast(z1), v2 = (yd.z + YO[4 * q + 2] * eat) * silu_fast(z2), v3 = (yd.w + YO[4 * q + 3] * eat) * silu_fast(z3);
;                 y[tb][pb][4 * q] = v0; y[tb][pb][4 * q + 1] = v1; y[tb][pb][4 * q + 2] = v2; y[tb][pb][4 * q + 3] = v3; ssq += v0 * v0 + v1 * v1 + v2 * v2 + v3 * v3; }
	v_lshlrev_b32_e32 v218, 16, v96
	v_and_b32_e32 v219, 0xffff0000, v96
	v_lshlrev_b32_e32 v220, 16, v97
	v_and_b32_e32 v221, 0xffff0000, v97
	v_fma_f32 v124, v216, v14, v86
	v_mul_f32_e32 v50, 0xbfb8aa3b, v218
	v_exp_f32_e32 v50, v50
	s_nop 0
	v_add_f32_e32 v50, 1.0, v50
	v_div_scale_f32 v51, s[8:9], v50, v50, v218
	v_rcp_f32_e32 v52, v51
	s_nop 0
	v_fma_f32 v53, -v51, v52, 1.0
	v_fmac_f32_e32 v52, v53, v52
	v_div_scale_f32 v53, vcc, v218, v50, v218
	v_mul_f32_e32 v66, v53, v52
	v_fma_f32 v122, -v51, v66, v53
	v_fmac_f32_e32 v66, v122, v52
	v_fma_f32 v51, -v51, v66, v53
	v_div_fmas_f32 v51, v51, v52, v66
	v_div_fixup_f32 v123, v51, v50, v218
	v_mul_f32_e32 v137, v124, v123
	v_fmac_f32_e32 v217, v137, v137
	v_fma_f32 v124, v216, v15, v87
	v_mul_f32_e32 v50, 0xbfb8aa3b, v219
	v_exp_f32_e32 v50, v50
	s_nop 0
	v_add_f32_e32 v50, 1.0, v50
	v_div_scale_f32 v51, s[8:9], v50, v50, v219
	v_rcp_f32_e32 v52, v51
	s_nop 0
	v_fma_f32 v53, -v51, v52, 1.0
	v_fmac_f32_e32 v52, v53, v52
	v_div_scale_f32 v53, vcc, v219, v50, v219
	v_mul_f32_e32 v66, v53, v52
	v_fma_f32 v122, -v51, v66, v53
	v_fmac_f32_e32 v66, v122, v52
	v_fma_f32 v51, -v51, v66, v53
	v_div_fmas_f32 v51, v51, v52, v66
	v_div_fixup_f32 v123, v51, v50, v219
	v_mul_f32_e32 v138, v124, v123
	v_fmac_f32_e32 v217, v138, v138
	v_fma_f32 v124, v216, v16, v88
	v_mul_f32_e32 v50, 0xbfb8aa3b, v220
	v_exp_f32_e32 v50, v50
	s_nop 0
	v_add_f32_e32 v50, 1.0, v50
	v_div_scale_f32 v51, s[8:9], v50, v50, v220
	v_rcp_f32_e32 v52, v51
	s_nop 0
	v_fma_f32 v53, -v51, v52, 1.0
	v_fmac_f32_e32 v52, v53, v52
	v_div_scale_f32 v53, vcc, v220, v50, v220
	v_mul_f32_e32 v66, v53, v52
	v_fma_f32 v122, -v51, v66, v53
	v_fmac_f32_e32 v66, v122, v52
	v_fma_f32 v51, -v51, v66, v53
	v_div_fmas_f32 v51, v51, v52, v66
	v_div_fixup_f32 v123, v51, v50, v220
	v_mul_f32_e32 v139, v124, v123
	v_fmac_f32_e32 v217, v139, v139
	v_fma_f32 v124, v216, v17, v89
	v_mul_f32_e32 v50, 0xbfb8aa3b, v221
	v_exp_f32_e32 v50, v50
	s_nop 0
	v_add_f32_e32 v50, 1.0, v50
	v_div_scale_f32 v51, s[8:9], v50, v50, v221
	v_rcp_f32_e32 v52, v51
	s_nop 0
	v_fma_f32 v53, -v51, v52, 1.0
	v_fmac_f32_e32 v52, v53, v52
	v_div_scale_f32 v53, vcc, v221, v50, v221
	v_mul_f32_e32 v66, v53, v52
	v_fma_f32 v122, -v51, v66, v53
	v_fmac_f32_e32 v66, v122, v52
	v_fma_f32 v51, -v51, v66, v53
	v_div_fmas_f32 v51, v51, v52, v66
	v_div_fixup_f32 v123, v51, v50, v221
	v_mul_f32_e32 v140, v124, v123
	v_fmac_f32_e32 v217, v140, v140
	s_waitcnt vmcnt(11)
	v_mfma_f32_32x32x16_bf16 v[2:17], v[18:21], v[34:37], 0
	s_waitcnt vmcnt(10)
	v_mfma_f32_32x32x16_bf16 v[2:17], v[22:25], v[38:41], v[2:17]
	s_waitcnt vmcnt(9)
	v_mfma_f32_32x32x16_bf16 v[2:17], v[26:29], v[42:45], v[2:17]
	s_waitcnt vmcnt(8)
	v_mfma_f32_32x32x16_bf16 v[2:17], v[30:33], v[46:49], v[2:17]
	s_nop 7
	v_mov_b32_e32 v233, 0
	v_or_b32_e32 v232, s11, v64
	v_lshlrev_b64 v[234:235], 5, v[232:233]
	v_lshl_add_u64 v[234:235], s[4:5], 0, v[234:235]
	v_lshlrev_b64 v[236:237], 8, v[232:233]
	v_lshl_add_u64 v[236:237], v[56:57], 0, v[236:237]
	v_lshlrev_b64 v[238:239], 11, v[232:233]
	v_lshl_add_u64 v[238:239], v[68:69], 0, v[238:239]
	v_mad_i64_i32 v[240:241], s[8:9], v232, s88, v[70:71]
	global_load_dword v193, v[234:235], off
	global_load_dwordx4 v[34:37], v[236:237], off offset:0
	global_load_dwordx4 v[38:41], v[236:237], off offset:32
	global_load_dwordx4 v[42:45], v[236:237], off offset:64
	global_load_dwordx4 v[46:49], v[236:237], off offset:96
	global_load_dwordx4 v[18:21], v[222:223], off offset:0
	global_load_dwordx4 v[22:25], v[222:223], off offset:32
	global_load_dwordx4 v[26:29], v[222:223], off offset:64
	global_load_dwordx4 v[30:33], v[222:223], off offset:96
	global_load_dwordx4 v[74:77], v[238:239], off offset:0
	global_load_dwordx4 v[78:81], v[238:239], off offset:32
	global_load_dwordx4 v[82:85], v[238:239], off offset:64
	global_load_dwordx4 v[86:89], v[238:239], off offset:96
	global_load_dwordx2 v[90:91], v[240:241], off offset:0
	global_load_dwordx2 v[92:93], v[240:241], off offset:16
	global_load_dwordx2 v[94:95], v[240:241], off offset:32
	global_load_dwordx2 v[96:97], v[240:241], off offset:48
	s_nop 15
	s_waitcnt vmcnt(20)
	v_lshlrev_b32_e32 v218, 16, v114
	v_and_b32_e32 v219, 0xffff0000, v114
	v_lshlrev_b32_e32 v220, 16, v115
	v_and_b32_e32 v221, 0xffff0000, v115
	v_fma_f32 v124, v216, v2, v98
	v_mul_f32_e32 v50, 0xbfb8aa3b, v218
	v_exp_f32_e32 v50, v50
	s_nop 0
	v_add_f32_e32 v50, 1.0, v50
	v_div_scale_f32 v51, s[8:9], v50, v50, v218
	v_rcp_f32_e32 v52, v51
	s_nop 0
	v_fma_f32 v53, -v51, v52, 1.0
	v_fmac_f32_e32 v52, v53, v52
	v_div_scale_f32 v53, vcc, v218, v50, v218
	v_mul_f32_e32 v66, v53, v52
	v_fma_f32 v122, -v51, v66, v53
	v_fmac_f32_e32 v66, v122, v52
	v_fma_f32 v51, -v51, v66, v53
	v_div_fmas_f32 v51, v51, v52, v66
	v_div_fixup_f32 v123, v51, v50, v218
	v_mul_f32_e32 v141, v124, v123
	v_fmac_f32_e32 v217, v141, v141
	v_fma_f32 v124, v216, v3, v99
	v_mul_f32_e32 v50, 0xbfb8aa3b, v219
	v_exp_f32_e32 v50, v50
	s_nop 0
	v_add_f32_e32 v50, 1.0, v50
	v_div_scale_f32 v51, s[8:9], v50, v50, v219
	v_rcp_f32_e32 v52, v51
	s_nop 0
	v_fma_f32 v53, -v51, v52, 1.0
	v_fmac_f32_e32 v52, v53, v52
	v_div_scale_f32 v53, vcc, v219, v50, v219
	v_mul_f32_e32 v66, v53, v52
	v_fma_f32 v122, -v51, v66, v53
	v_fmac_f32_e32 v66, v122, v52
	v_fma_f32 v51, -v51, v66, v53
	v_div_fmas_f32 v51, v51, v52, v66
	v_div_fixup_f32 v123, v51, v50, v219
	v_mul_f32_e32 v142, v124, v123
	v_fmac_f32_e32 v217, v142, v142
	v_fma_f32 v124, v216, v4, v100
	v_mul_f32_e32 v50, 0xbfb8aa3b, v220
	v_exp_f32_e32 v50, v50
	s_nop 0
	v_add_f32_e32 v50, 1.0, v50
	v_div_scale_f32 v51, s[8:9], v50, v50, v220
	v_rcp_f32_e32 v52, v51
	s_nop 0
	v_fma_f32 v53, -v51, v52, 1.0
	v_fmac_f32_e32 v52, v53, v52
	v_div_scale_f32 v53, vcc, v220, v50, v220
	v_mul_f32_e32 v66, v53, v52
	v_fma_f32 v122, -v51, v66, v53
	v_fmac_f32_e32 v66, v122, v52
	v_fma_f32 v51, -v51, v66, v53
	v_div_fmas_f32 v51, v51, v52, v66
	v_div_fixup_f32 v123, v51, v50, v220
	v_mul_f32_e32 v143, v124, v123
	v_fmac_f32_e32 v217, v143, v143
	v_fma_f32 v124, v216, v5, v101
	v_mul_f32_e32 v50, 0xbfb8aa3b, v221
	v_exp_f32_e32 v50, v50
	s_nop 0
	v_add_f32_e32 v50, 1.0, v50
	v_div_scale_f32 v51, s[8:9], v50, v50, v221
	v_rcp_f32_e32 v52, v51
	s_nop 0
	v_fma_f32 v53, -v51, v52, 1.0
	v_fmac_f32_e32 v52, v53, v52
	v_div_scale_f32 v53, vcc, v221, v50, v221
	v_mul_f32_e32 v66, v53, v52
	v_fma_f32 v122, -v51, v66, v53
	v_fmac_f32_e32 v66, v122, v52
	v_fma_f32 v51, -v51, v66, v53
	v_div_fmas_f32 v51, v51, v52, v66
	v_div_fixup_f32 v123, v51, v50, v221
	v_mul_f32_e32 v144, v124, v123
	v_fmac_f32_e32 v217, v144, v144
	s_waitcnt vmcnt(19)
;     DEVI bf16_t* proj() const { return (bf16_t*)(ws + WS_PROJ); }
;     DEVI float* ydg() const { return (float*)(ws + WS_YZ); }
; DEVI float silu_fast(float x) { return x / (1.f + __expf(-x)); }
; DEVI void ssd_y_unit(const P& p, int l, int ci, LAS unsigned char* lds, int tid, int wave, int lane) {
;     ...
;             for (int q = 0; q < 4; ++q) { const int p0 = wave * 64 + 32 * pb + 8 * q + 4 * hh;
;                 const float4 yd = *(const float4*)(p.ydg() + r * 512 + p0); const uint2 zz = *(const uint2*)(p.proj() + r * NP + O_Z + p0);
;                 const float z0 = __uint_as_float(zz.x << 16), z1 = __uint_as_float(zz.x & 0xffff0000u), z2 = __uint_as_float(zz.y << 16), z3 = __uint_as_float(zz.y & 0xffff0000u);
;                 const float v0 = (yd.x + YO[4 * q] * eat) * silu_fast(z0), v1 = (yd.y + YO[4 * q + 1] * eat) * silu_fast(z1), v2 = (yd.z + YO[4 * q + 2] * eat) * silu_fast(z2), v3 = (yd.w + YO[4 * q + 3] * eat) * silu_fast(z3);
;                 y[tb][pb][4 * q] = v0; y[tb][pb][4 * q + 1] = v1; y[tb][pb][4 * q + 2] = v2; y[tb][pb][4 * q + 3] = v3; ssq += v0 * v0 + v1 * v1 + v2 * v2 + v3 * v3; }
	v_lshlrev_b32_e32 v218, 16, v116
	v_and_b32_e32 v219, 0xffff0000, v116
	v_lshlrev_b32_e32 v220, 16, v117
	v_and_b32_e32 v221, 0xffff0000, v117
	v_fma_f32 v124, v216, v6, v102
	v_mul_f32_e32 v50, 0xbfb8aa3b, v218
	v_exp_f32_e32 v50, v50
	s_nop 0
	v_add_f32_e32 v50, 1.0, v50
	v_div_scale_f32 v51, s[8:9], v50, v50, v218
	v_rcp_f32_e32 v52, v51
	s_nop 0
	v_fma_f32 v53, -v51, v52, 1.0
	v_fmac_f32_e32 v52, v53, v52
	v_div_scale_f32 v53, vcc, v218, v50, v218
	v_mul_f32_e32 v66, v53, v52
	v_fma_f32 v122, -v51, v66, v53
	v_fmac_f32_e32 v66, v122, v52
	v_fma_f32 v51, -v51, v66, v53
	v_div_fmas_f32 v51, v51, v52, v66
	v_div_fixup_f32 v123, v51, v50, v218
	v_mul_f32_e32 v145, v124, v123
	v_fmac_f32_e32 v217, v145, v145
	v_fma_f32 v124, v216, v7, v103
	v_mul_f32_e32 v50, 0xbfb8aa3b, v219
	v_exp_f32_e32 v50, v50
	s_nop 0
	v_add_f32_e32 v50, 1.0, v50
	v_div_scale_f32 v51, s[8:9], v50, v50, v219
	v_rcp_f32_e32 v52, v51
	s_nop 0
	v_fma_f32 v53, -v51, v52, 1.0
	v_fmac_f32_e32 v52, v53, v52
	v_div_scale_f32 v53, vcc, v219, v50, v219
	v_mul_f32_e32 v66, v53, v52
	v_fma_f32 v122, -v51, v66, v53
	v_fmac_f32_e32 v66, v122, v52
	v_fma_f32 v51, -v51, v66, v53
	v_div_fmas_f32 v51, v51, v52, v66
	v_div_fixup_f32 v123, v51, v50, v219
	v_mul_f32_e32 v146, v124, v123
	v_fmac_f32_e32 v217, v146, v146
	v_fma_f32 v124, v216, v8, v104
	v_mul_f32_e32 v50, 0xbfb8aa3b, v220
	v_exp_f32_e32 v50, v50
	s_nop 0
	v_add_f32_e32 v50, 1.0, v50
	v_div_scale_f32 v51, s[8:9], v50, v50, v220
	v_rcp_f32_e32 v52, v51
	s_nop 0
	v_fma_f32 v53, -v51, v52, 1.0
	v_fmac_f32_e32 v52, v53, v52
	v_div_scale_f32 v53, vcc, v220, v50, v220
	v_mul_f32_e32 v66, v53, v52
	v_fma_f32 v122, -v51, v66, v53
	v_fmac_f32_e32 v66, v122, v52
	v_fma_f32 v51, -v51, v66, v53
	v_div_fmas_f32 v51, v51, v52, v66
	v_div_fixup_f32 v123, v51, v50, v220
	v_mul_f32_e32 v147, v124, v123
	v_fmac_f32_e32 v217, v147, v147
	v_fma_f32 v124, v216, v9, v105
	v_mul_f32_e32 v50, 0xbfb8aa3b, v221
	v_exp_f32_e32 v50, v50
	s_nop 0
	v_add_f32_e32 v50, 1.0, v50
	v_div_scale_f32 v51, s[8:9], v50, v50, v221
	v_rcp_f32_e32 v52, v51
	s_nop 0
	v_fma_f32 v53, -v51, v52, 1.0
	v_fmac_f32_e32 v52, v53, v52
	v_div_scale_f32 v53, vcc, v221, v50, v221
	v_mul_f32_e32 v66, v53, v52
	v_fma_f32 v122, -v51, v66, v53
	v_fmac_f32_e32 v66, v122, v52
	v_fma_f32 v51, -v51, v66, v53
	v_div_fmas_f32 v51, v51, v52, v66
	v_div_fixup_f32 v123, v51, v50, v221
	v_mul_f32_e32 v148, v124, v123
	v_fmac_f32_e32 v217, v148, v148
	s_waitcnt vmcnt(18)
	v_lshlrev_b32_e32 v218, 16, v118
	v_and_b32_e32 v219, 0xffff0000, v118
	v_lshlrev_b32_e32 v220, 16, v119
	v_and_b32_e32 v221, 0xffff0000, v119
	v_fma_f32 v124, v216, v10, v106
	v_mul_f32_e32 v50, 0xbfb8aa3b, v218
	v_exp_f32_e32 v50, v50
	s_nop 0
	v_add_f32_e32 v50, 1.0, v50
	v_div_scale_f32 v51, s[8:9], v50, v50, v218
	v_rcp_f32_e32 v52, v51
	s_nop 0
	v_fma_f32 v53, -v51, v52, 1.0
	v_fmac_f32_e32 v52, v53, v52
	v_div_scale_f32 v53, vcc, v218, v50, v218
	v_mul_f32_e32 v66, v53, v52
	v_fma_f32 v122, -v51, v66, v53
	v_fmac_f32_e32 v66, v122, v52
	v_fma_f32 v51, -v51, v66, v53
	v_div_fmas_f32 v51, v51, v52, v66
	v_div_fixup_f32 v123, v51, v50, v218
	v_mul_f32_e32 v149, v124, v123
	v_fmac_f32_e32 v217, v149, v149
	v_fma_f32 v124, v216, v11, v107
	v_mul_f32_e32 v50, 0xbfb8aa3b, v219
	v_exp_f32_e32 v50, v50
	s_nop 0
	v_add_f32_e32 v50, 1.0, v50
	v_div_scale_f32 v51, s[8:9], v50, v50, v219
	v_rcp_f32_e32 v52, v51
	s_nop 0
	v_fma_f32 v53, -v51, v52, 1.0
	v_fmac_f32_e32 v52, v53, v52
	v_div_scale_f32 v53, vcc, v219, v50, v219
	v_mul_f32_e32 v66, v53, v52
	v_fma_f32 v122, -v51, v66, v53
	v_fmac_f32_e32 v66, v122, v52
	v_fma_f32 v51, -v51, v66, v53
	v_div_fmas_f32 v51, v51, v52, v66
	v_div_fixup_f32 v123, v51, v50, v219
	v_mul_f32_e32 v150, v124, v123
	v_fmac_f32_e32 v217, v150, v150
	v_fma_f32 v124, v216, v12, v108
	v_mul_f32_e32 v50, 0xbfb8aa3b, v220
	v_exp_f32_e32 v50, v50
	s_nop 0
	v_add_f32_e32 v50, 1.0, v50
	v_div_scale_f32 v51, s[8:9], v50, v50, v220
	v_rcp_f32_e32 v52, v51
	s_nop 0
	v_fma_f32 v53, -v51, v52, 1.0
	v_fmac_f32_e32 v52, v53, v52
	v_div_scale_f32 v53, vcc, v220, v50, v220
	v_mul_f32_e32 v66, v53, v52
	v_fma_f32 v122, -v51, v66, v53
	v_fmac_f32_e32 v66, v122, v52
	v_fma_f32 v51, -v51, v66, v53
	v_div_fmas_f32 v51, v51, v52, v66
	v_div_fixup_f32 v123, v51, v50, v220
	v_mul_f32_e32 v151, v124, v123
	v_fmac_f32_e32 v217, v151, v151
	v_fma_f32 v124, v216, v13, v109
	v_mul_f32_e32 v50, 0xbfb8aa3b, v221
	v_exp_f32_e32 v50, v50
	s_nop 0
	v_add_f32_e32 v50, 1.0, v50
	v_div_scale_f32 v51, s[8:9], v50, v50, v221
	v_rcp_f32_e32 v52, v51
	s_nop 0
	v_fma_f32 v53, -v51, v52, 1.0
	v_fmac_f32_e32 v52, v53, v52
	v_div_scale_f32 v53, vcc, v221, v50, v221
	v_mul_f32_e32 v66, v53, v52
	v_fma_f32 v122, -v51, v66, v53
	v_fmac_f32_e32 v66, v122, v52
	v_fma_f32 v51, -v51, v66, v53
	v_div_fmas_f32 v51, v51, v52, v66
	v_div_fixup_f32 v123, v51, v50, v221
	v_mul_f32_e32 v152, v124, v123
	v_fmac_f32_e32 v217, v152, v152
	s_waitcnt vmcnt(17)
;     DEVI bf16_t* proj() const { return (bf16_t*)(ws + WS_PROJ); }
;     DEVI bf16_t* prevb() const { return (bf16_t*)(ws + WS_XBC); }
;     DEVI float* acum() const { return (float*)(ws + WS_ACUM); }
;     DEVI bf16_t* cact() const { return (bf16_t*)(ws + WS_CB); }
;     DEVI float* ydg() const { return (float*)(ws + WS_YZ); }
; DEVI float silu_fast(float x) { return x / (1.f + __expf(-x)); }
; DEVI void ssd_y_unit(const P& p, int l, int ci, LAS unsigned char* lds, int tid, int wave, int lane) {
;     ...
;         const size_t r = (size_t)r0 + 32 * tb + c32; const float eat = __expf(p.acum()[r * 8 + wave]); float ssq = 0.f;
; #pragma unroll
;         for (int pb = 0; pb < 2; ++pb) {
;             f32x16_t YO = z16;
; #pragma unroll
;             for (int kk = 0; kk < 4; ++kk) {
;                 const bf16x8_t a = *(const bf16x8_t*)(p.prevb() + ((size_t)(ci * 8 + wave) * 64 + 32 * pb + c32) * 64 + 16 * kk + 8 * hh);
;                 const bf16x8_t b = *(const bf16x8_t*)(p.cact() + r * 128 + g * 64 + 16 * kk + 8 * hh);
;                 YO = __builtin_amdgcn_mfma_f32_32x32x16_bf16(a, b, YO, 0, 0, 0);
;             }
;     ...
;             for (int q = 0; q < 4; ++q) { const int p0 = wave * 64 + 32 * pb + 8 * q + 4 * hh;
;                 const float4 yd = *(const float4*)(p.ydg() + r * 512 + p0); const uint2 zz = *(const uint2*)(p.proj() + r * NP + O_Z + p0);
;                 const float z0 = __uint_as_float(zz.x << 16), z1 = __uint_as_float(zz.x & 0xffff0000u), z2 = __uint_as_float(zz.y << 16), z3 = __uint_as_float(zz.y & 0xffff0000u);
;                 const float v0 = (yd.x + YO[4 * q] * eat) * silu_fast(z0), v1 = (yd.y + YO[4 * q + 1] * eat) * silu_fast(z1), v2 = (yd.z + YO[4 * q + 2] * eat) * silu_fast(z2), v3 = (yd.w + YO[4 * q + 3] * eat) * silu_fast(z3);
;                 y[tb][pb][4 * q] = v0; y[tb][pb][4 * q + 1] = v1; y[tb][pb][4 * q + 2] = v2; y[tb][pb][4 * q + 3] = v3; ssq += v0 * v0 + v1 * v1 + v2 * v2 + v3 * v3; }
;         }
;         ssq += __shfl_xor(ssq, 32);
;         if (hh == 0) part[wave * 64 + 32 * tb + c32] = ssq;
	v_lshlrev_b32_e32 v218, 16, v120
	v_and_b32_e32 v219, 0xffff0000, v120
	v_lshlrev_b32_e32 v220, 16, v121
	v_and_b32_e32 v221, 0xffff0000, v121
	v_fma_f32 v124, v216, v14, v110
	v_mul_f32_e32 v50, 0xbfb8aa3b, v218
	v_exp_f32_e32 v50, v50
	s_nop 0
	v_add_f32_e32 v50, 1.0, v50
	v_div_scale_f32 v51, s[8:9], v50, v50, v218
	v_rcp_f32_e32 v52, v51
	s_nop 0
	v_fma_f32 v53, -v51, v52, 1.0
	v_fmac_f32_e32 v52, v53, v52
	v_div_scale_f32 v53, vcc, v218, v50, v218
	v_mul_f32_e32 v66, v53, v52
	v_fma_f32 v122, -v51, v66, v53
	v_fmac_f32_e32 v66, v122, v52
	v_fma_f32 v51, -v51, v66, v53
	v_div_fmas_f32 v51, v51, v52, v66
	v_div_fixup_f32 v123, v51, v50, v218
	v_mul_f32_e32 v153, v124, v123
	v_fmac_f32_e32 v217, v153, v153
	v_fma_f32 v124, v216, v15, v111
	v_mul_f32_e32 v50, 0xbfb8aa3b, v219
	v_exp_f32_e32 v50, v50
	s_nop 0
	v_add_f32_e32 v50, 1.0, v50
	v_div_scale_f32 v51, s[8:9], v50, v50, v219
	v_rcp_f32_e32 v52, v51
	s_nop 0
	v_fma_f32 v53, -v51, v52, 1.0
	v_fmac_f32_e32 v52, v53, v52
	v_div_scale_f32 v53, vcc, v219, v50, v219
	v_mul_f32_e32 v66, v53, v52
	v_fma_f32 v122, -v51, v66, v53
	v_fmac_f32_e32 v66, v122, v52
	v_fma_f32 v51, -v51, v66, v53
	v_div_fmas_f32 v51, v51, v52, v66
	v_div_fixup_f32 v123, v51, v50, v219
	v_mul_f32_e32 v154, v124, v123
	v_fmac_f32_e32 v217, v154, v154
	v_fma_f32 v124, v216, v16, v112
	v_mul_f32_e32 v50, 0xbfb8aa3b, v220
	v_exp_f32_e32 v50, v50
	s_nop 0
	v_add_f32_e32 v50, 1.0, v50
	v_div_scale_f32 v51, s[8:9], v50, v50, v220
	v_rcp_f32_e32 v52, v51
	s_nop 0
	v_fma_f32 v53, -v51, v52, 1.0
	v_fmac_f32_e32 v52, v53, v52
	v_div_scale_f32 v53, vcc, v220, v50, v220
	v_mul_f32_e32 v66, v53, v52
	v_fma_f32 v122, -v51, v66, v53
	v_fmac_f32_e32 v66, v122, v52
	v_fma_f32 v51, -v51, v66, v53
	v_div_fmas_f32 v51, v51, v52, v66
	v_div_fixup_f32 v123, v51, v50, v220
	v_mul_f32_e32 v155, v124, v123
	v_fmac_f32_e32 v217, v155, v155
	v_fma_f32 v124, v216, v17, v113
	v_mul_f32_e32 v50, 0xbfb8aa3b, v221
	v_exp_f32_e32 v50, v50
	s_nop 0
	v_add_f32_e32 v50, 1.0, v50
	v_div_scale_f32 v51, s[8:9], v50, v50, v221
	v_rcp_f32_e32 v52, v51
	s_nop 0
	v_fma_f32 v53, -v51, v52, 1.0
	v_fmac_f32_e32 v52, v53, v52
	v_div_scale_f32 v53, vcc, v221, v50, v221
	v_mul_f32_e32 v66, v53, v52
	v_fma_f32 v122, -v51, v66, v53
	v_fmac_f32_e32 v66, v122, v52
	v_fma_f32 v51, -v51, v66, v53
	v_div_fmas_f32 v51, v51, v52, v66
	v_div_fixup_f32 v123, v51, v50, v221
	v_mul_f32_e32 v156, v124, v123
	v_fmac_f32_e32 v217, v156, v156
	s_nop 1
	ds_bpermute_b32 v124, v208, v217
	s_waitcnt lgkmcnt(0)
	v_add_f32_e32 v217, v217, v124
	s_and_saveexec_b64 s[8:9], s[2:3]
	ds_write_b32 v1, v217
	s_or_b64 exec, exec, s[8:9]
	s_waitcnt vmcnt(16)
	v_mul_f32_e32 v193, 0x3fb8aa3b, v193
	v_exp_f32_e32 v193, v193
	v_mov_b32_e32 v217, 0
	s_waitcnt vmcnt(11)
	v_mfma_f32_32x32x16_bf16 v[2:17], v[18:21], v[34:37], 0
	s_waitcnt vmcnt(10)
	v_mfma_f32_32x32x16_bf16 v[2:17], v[22:25], v[38:41], v[2:17]
	s_waitcnt vmcnt(9)
	v_mfma_f32_32x32x16_bf16 v[2:17], v[26:29], v[42:45], v[2:17]
	s_waitcnt vmcnt(8)
	v_mfma_f32_32x32x16_bf16 v[2:17], v[30:33], v[46:49], v[2:17]
	s_nop 7
	global_load_dwordx4 v[18:21], v[194:195], off offset:0
	global_load_dwordx4 v[22:25], v[194:195], off offset:32
	global_load_dwordx4 v[26:29], v[194:195], off offset:64
	global_load_dwordx4 v[30:33], v[194:195], off offset:96
	global_load_dwordx4 v[98:101], v[238:239], off offset:128
	global_load_dwordx4 v[102:105], v[238:239], off offset:160
	global_load_dwordx4 v[106:109], v[238:239], off offset:192
	global_load_dwordx4 v[110:113], v[238:239], off offset:224
	global_load_dwordx2 v[114:115], v[240:241], off offset:64
	global_load_dwordx2 v[116:117], v[240:241], off offset:80
	global_load_dwordx2 v[118:119], v[240:241], off offset:96
	global_load_dwordx2 v[120:121], v[240:241], off offset:112
	s_nop 15
	s_waitcnt vmcnt(15)
	v_lshlrev_b32_e32 v218, 16, v90
	v_and_b32_e32 v219, 0xffff0000, v90
	v_lshlrev_b32_e32 v220, 16, v91
	v_and_b32_e32 v221, 0xffff0000, v91
	v_fma_f32 v124, v193, v2, v74
	v_mul_f32_e32 v50, 0xbfb8aa3b, v218
	v_exp_f32_e32 v50, v50
	s_nop 0
	v_add_f32_e32 v50, 1.0, v50
	v_div_scale_f32 v51, s[8:9], v50, v50, v218
	v_rcp_f32_e32 v52, v51
	s_nop 0
	v_fma_f32 v53, -v51, v52, 1.0
	v_fmac_f32_e32 v52, v53, v52
	v_div_scale_f32 v53, vcc, v218, v50, v218
	v_mul_f32_e32 v66, v53, v52
	v_fma_f32 v122, -v51, v66, v53
	v_fmac_f32_e32 v66, v122, v52
	v_fma_f32 v51, -v51, v66, v53
	v_div_fmas_f32 v51, v51, v52, v66
	v_div_fixup_f32 v123, v51, v50, v218
	v_mul_f32_e32 v157, v124, v123
	v_fmac_f32_e32 v217, v157, v157
	v_fma_f32 v124, v193, v3, v75
	v_mul_f32_e32 v50, 0xbfb8aa3b, v219
	v_exp_f32_e32 v50, v50
	s_nop 0
	v_add_f32_e32 v50, 1.0, v50
	v_div_scale_f32 v51, s[8:9], v50, v50, v219
	v_rcp_f32_e32 v52, v51
	s_nop 0
	v_fma_f32 v53, -v51, v52, 1.0
	v_fmac_f32_e32 v52, v53, v52
	v_div_scale_f32 v53, vcc, v219, v50, v219
	v_mul_f32_e32 v66, v53, v52
	v_fma_f32 v122, -v51, v66, v53
	v_fmac_f32_e32 v66, v122, v52
	v_fma_f32 v51, -v51, v66, v53
	v_div_fmas_f32 v51, v51, v52, v66
	v_div_fixup_f32 v123, v51, v50, v219
	v_mul_f32_e32 v158, v124, v123
	v_fmac_f32_e32 v217, v158, v158
	v_fma_f32 v124, v193, v4, v76
	v_mul_f32_e32 v50, 0xbfb8aa3b, v220
	v_exp_f32_e32 v50, v50
	s_nop 0
	v_add_f32_e32 v50, 1.0, v50
	v_div_scale_f32 v51, s[8:9], v50, v50, v220
	v_rcp_f32_e32 v52, v51
	s_nop 0
	v_fma_f32 v53, -v51, v52, 1.0
	v_fmac_f32_e32 v52, v53, v52
	v_div_scale_f32 v53, vcc, v220, v50, v220
	v_mul_f32_e32 v66, v53, v52
	v_fma_f32 v122, -v51, v66, v53
	v_fmac_f32_e32 v66, v122, v52
	v_fma_f32 v51, -v51, v66, v53
	v_div_fmas_f32 v51, v51, v52, v66
	v_div_fixup_f32 v123, v51, v50, v220
	v_mul_f32_e32 v159, v124, v123
	v_fmac_f32_e32 v217, v159, v159
	v_fma_f32 v124, v193, v5, v77
	v_mul_f32_e32 v50, 0xbfb8aa3b, v221
	v_exp_f32_e32 v50, v50
	s_nop 0
	v_add_f32_e32 v50, 1.0, v50
	v_div_scale_f32 v51, s[8:9], v50, v50, v221
	v_rcp_f32_e32 v52, v51
	s_nop 0
	v_fma_f32 v53, -v51, v52, 1.0
	v_fmac_f32_e32 v52, v53, v52
	v_div_scale_f32 v53, vcc, v221, v50, v221
	v_mul_f32_e32 v66, v53, v52
	v_fma_f32 v122, -v51, v66, v53
	v_fmac_f32_e32 v66, v122, v52
	v_fma_f32 v51, -v51, v66, v53
	v_div_fmas_f32 v51, v51, v52, v66
	v_div_fixup_f32 v123, v51, v50, v221
	v_mul_f32_e32 v160, v124, v123
	v_fmac_f32_e32 v217, v160, v160
	s_waitcnt vmcnt(14)
;     DEVI bf16_t* proj() const { return (bf16_t*)(ws + WS_PROJ); }
;     DEVI float* ydg() const { return (float*)(ws + WS_YZ); }
; DEVI float silu_fast(float x) { return x / (1.f + __expf(-x)); }
; DEVI void ssd_y_unit(const P& p, int l, int ci, LAS unsigned char* lds, int tid, int wave, int lane) {
;     ...
;             for (int q = 0; q < 4; ++q) { const int p0 = wave * 64 + 32 * pb + 8 * q + 4 * hh;
;                 const float4 yd = *(const float4*)(p.ydg() + r * 512 + p0); const uint2 zz = *(const uint2*)(p.proj() + r * NP + O_Z + p0);
;                 const float z0 = __uint_as_float(zz.x << 16), z1 = __uint_as_float(zz.x & 0xffff0000u), z2 = __uint_as_float(zz.y << 16), z3 = __uint_as_float(zz.y & 0xffff0000u);
;                 const float v0 = (yd.x + YO[4 * q] * eat) * silu_fast(z0), v1 = (yd.y + YO[4 * q + 1] * eat) * silu_fast(z1), v2 = (yd.z + YO[4 * q + 2] * eat) * silu_fast(z2), v3 = (yd.w + YO[4 * q + 3] * eat) * silu_fast(z3);
;                 y[tb][pb][4 * q] = v0; y[tb][pb][4 * q + 1] = v1; y[tb][pb][4 * q + 2] = v2; y[tb][pb][4 * q + 3] = v3; ssq += v0 * v0 + v1 * v1 + v2 * v2 + v3 * v3; }
	v_lshlrev_b32_e32 v218, 16, v92
	v_and_b32_e32 v219, 0xffff0000, v92
	v_lshlrev_b32_e32 v220, 16, v93
	v_and_b32_e32 v221, 0xffff0000, v93
	v_fma_f32 v124, v193, v6, v78
	v_mul_f32_e32 v50, 0xbfb8aa3b, v218
	v_exp_f32_e32 v50, v50
	s_nop 0
	v_add_f32_e32 v50, 1.0, v50
	v_div_scale_f32 v51, s[8:9], v50, v50, v218
	v_rcp_f32_e32 v52, v51
	s_nop 0
	v_fma_f32 v53, -v51, v52, 1.0
	v_fmac_f32_e32 v52, v53, v52
	v_div_scale_f32 v53, vcc, v218, v50, v218
	v_mul_f32_e32 v66, v53, v52
	v_fma_f32 v122, -v51, v66, v53
	v_fmac_f32_e32 v66, v122, v52
	v_fma_f32 v51, -v51, v66, v53
	v_div_fmas_f32 v51, v51, v52, v66
	v_div_fixup_f32 v123, v51, v50, v218
	v_mul_f32_e32 v161, v124, v123
	v_fmac_f32_e32 v217, v161, v161
	v_fma_f32 v124, v193, v7, v79
	v_mul_f32_e32 v50, 0xbfb8aa3b, v219
	v_exp_f32_e32 v50, v50
	s_nop 0
	v_add_f32_e32 v50, 1.0, v50
	v_div_scale_f32 v51, s[8:9], v50, v50, v219
	v_rcp_f32_e32 v52, v51
	s_nop 0
	v_fma_f32 v53, -v51, v52, 1.0
	v_fmac_f32_e32 v52, v53, v52
	v_div_scale_f32 v53, vcc, v219, v50, v219
	v_mul_f32_e32 v66, v53, v52
	v_fma_f32 v122, -v51, v66, v53
	v_fmac_f32_e32 v66, v122, v52
	v_fma_f32 v51, -v51, v66, v53
	v_div_fmas_f32 v51, v51, v52, v66
	v_div_fixup_f32 v123, v51, v50, v219
	v_mul_f32_e32 v162, v124, v123
	v_fmac_f32_e32 v217, v162, v162
	v_fma_f32 v124, v193, v8, v80
	v_mul_f32_e32 v50, 0xbfb8aa3b, v220
	v_exp_f32_e32 v50, v50
	s_nop 0
	v_add_f32_e32 v50, 1.0, v50
	v_div_scale_f32 v51, s[8:9], v50, v50, v220
	v_rcp_f32_e32 v52, v51
	s_nop 0
	v_fma_f32 v53, -v51, v52, 1.0
	v_fmac_f32_e32 v52, v53, v52
	v_div_scale_f32 v53, vcc, v220, v50, v220
	v_mul_f32_e32 v66, v53, v52
	v_fma_f32 v122, -v51, v66, v53
	v_fmac_f32_e32 v66, v122, v52
	v_fma_f32 v51, -v51, v66, v53
	v_div_fmas_f32 v51, v51, v52, v66
	v_div_fixup_f32 v123, v51, v50, v220
	v_mul_f32_e32 v163, v124, v123
	v_fmac_f32_e32 v217, v163, v163
	v_fma_f32 v124, v193, v9, v81
	v_mul_f32_e32 v50, 0xbfb8aa3b, v221
	v_exp_f32_e32 v50, v50
	s_nop 0
	v_add_f32_e32 v50, 1.0, v50
	v_div_scale_f32 v51, s[8:9], v50, v50, v221
	v_rcp_f32_e32 v52, v51
	s_nop 0
	v_fma_f32 v53, -v51, v52, 1.0
	v_fmac_f32_e32 v52, v53, v52
	v_div_scale_f32 v53, vcc, v221, v50, v221
	v_mul_f32_e32 v66, v53, v52
	v_fma_f32 v122, -v51, v66, v53
	v_fmac_f32_e32 v66, v122, v52
	v_fma_f32 v51, -v51, v66, v53
	v_div_fmas_f32 v51, v51, v52, v66
	v_div_fixup_f32 v123, v51, v50, v221
	v_mul_f32_e32 v164, v124, v123
	v_fmac_f32_e32 v217, v164, v164
	s_waitcnt vmcnt(13)
	v_lshlrev_b32_e32 v218, 16, v94
	v_and_b32_e32 v219, 0xffff0000, v94
	v_lshlrev_b32_e32 v220, 16, v95
	v_and_b32_e32 v221, 0xffff0000, v95
	v_fma_f32 v124, v193, v10, v82
	v_mul_f32_e32 v50, 0xbfb8aa3b, v218
	v_exp_f32_e32 v50, v50
	s_nop 0
	v_add_f32_e32 v50, 1.0, v50
	v_div_scale_f32 v51, s[8:9], v50, v50, v218
	v_rcp_f32_e32 v52, v51
	s_nop 0
	v_fma_f32 v53, -v51, v52, 1.0
	v_fmac_f32_e32 v52, v53, v52
	v_div_scale_f32 v53, vcc, v218, v50, v218
	v_mul_f32_e32 v66, v53, v52
	v_fma_f32 v122, -v51, v66, v53
	v_fmac_f32_e32 v66, v122, v52
	v_fma_f32 v51, -v51, v66, v53
	v_div_fmas_f32 v51, v51, v52, v66
	v_div_fixup_f32 v123, v51, v50, v218
	v_mul_f32_e32 v165, v124, v123
	v_fmac_f32_e32 v217, v165, v165
	v_fma_f32 v124, v193, v11, v83
	v_mul_f32_e32 v50, 0xbfb8aa3b, v219
	v_exp_f32_e32 v50, v50
	s_nop 0
	v_add_f32_e32 v50, 1.0, v50
	v_div_scale_f32 v51, s[8:9], v50, v50, v219
	v_rcp_f32_e32 v52, v51
	s_nop 0
	v_fma_f32 v53, -v51, v52, 1.0
	v_fmac_f32_e32 v52, v53, v52
	v_div_scale_f32 v53, vcc, v219, v50, v219
	v_mul_f32_e32 v66, v53, v52
	v_fma_f32 v122, -v51, v66, v53
	v_fmac_f32_e32 v66, v122, v52
	v_fma_f32 v51, -v51, v66, v53
	v_div_fmas_f32 v51, v51, v52, v66
	v_div_fixup_f32 v123, v51, v50, v219
	v_mul_f32_e32 v166, v124, v123
	v_fmac_f32_e32 v217, v166, v166
	v_fma_f32 v124, v193, v12, v84
	v_mul_f32_e32 v50, 0xbfb8aa3b, v220
	v_exp_f32_e32 v50, v50
	s_nop 0
	v_add_f32_e32 v50, 1.0, v50
	v_div_scale_f32 v51, s[8:9], v50, v50, v220
	v_rcp_f32_e32 v52, v51
	s_nop 0
	v_fma_f32 v53, -v51, v52, 1.0
	v_fmac_f32_e32 v52, v53, v52
	v_div_scale_f32 v53, vcc, v220, v50, v220
	v_mul_f32_e32 v66, v53, v52
	v_fma_f32 v122, -v51, v66, v53
	v_fmac_f32_e32 v66, v122, v52
	v_fma_f32 v51, -v51, v66, v53
	v_div_fmas_f32 v51, v51, v52, v66
	v_div_fixup_f32 v123, v51, v50, v220
	v_mul_f32_e32 v167, v124, v123
	v_fmac_f32_e32 v217, v167, v167
	v_fma_f32 v124, v193, v13, v85
	v_mul_f32_e32 v50, 0xbfb8aa3b, v221
	v_exp_f32_e32 v50, v50
	s_nop 0
	v_add_f32_e32 v50, 1.0, v50
	v_div_scale_f32 v51, s[8:9], v50, v50, v221
	v_rcp_f32_e32 v52, v51
	s_nop 0
	v_fma_f32 v53, -v51, v52, 1.0
	v_fmac_f32_e32 v52, v53, v52
	v_div_scale_f32 v53, vcc, v221, v50, v221
	v_mul_f32_e32 v66, v53, v52
	v_fma_f32 v122, -v51, v66, v53
	v_fmac_f32_e32 v66, v122, v52
	v_fma_f32 v51, -v51, v66, v53
	v_div_fmas_f32 v51, v51, v52, v66
	v_div_fixup_f32 v123, v51, v50, v221
	v_mul_f32_e32 v168, v124, v123
	v_fmac_f32_e32 v217, v168, v168
	s_waitcnt vmcnt(12)
;     DEVI bf16_t* proj() const { return (bf16_t*)(ws + WS_PROJ); }
;     DEVI bf16_t* prevb() const { return (bf16_t*)(ws + WS_XBC); }
;     DEVI bf16_t* cact() const { return (bf16_t*)(ws + WS_CB); }
;     DEVI float* ydg() const { return (float*)(ws + WS_YZ); }
; DEVI float silu_fast(float x) { return x / (1.f + __expf(-x)); }
; DEVI void ssd_y_unit(const P& p, int l, int ci, LAS unsigned char* lds, int tid, int wave, int lane) {
;     ...
;             for (int kk = 0; kk < 4; ++kk) {
;                 const bf16x8_t a = *(const bf16x8_t*)(p.prevb() + ((size_t)(ci * 8 + wave) * 64 + 32 * pb + c32) * 64 + 16 * kk + 8 * hh);
;                 const bf16x8_t b = *(const bf16x8_t*)(p.cact() + r * 128 + g * 64 + 16 * kk + 8 * hh);
;                 YO = __builtin_amdgcn_mfma_f32_32x32x16_bf16(a, b, YO, 0, 0, 0);
;             }
; #pragma unroll
;             for (int q = 0; q < 4; ++q) { const int p0 = wave * 64 + 32 * pb + 8 * q + 4 * hh;
;                 const float4 yd = *(const float4*)(p.ydg() + r * 512 + p0); const uint2 zz = *(const uint2*)(p.proj() + r * NP + O_Z + p0);
;                 const float z0 = __uint_as_float(zz.x << 16), z1 = __uint_as_float(zz.x & 0xffff0000u), z2 = __uint_as_float(zz.y << 16), z3 = __uint_as_float(zz.y & 0xffff0000u);
;                 const float v0 = (yd.x + YO[4 * q] * eat) * silu_fast(z0), v1 = (yd.y + YO[4 * q + 1] * eat) * silu_fast(z1), v2 = (yd.z + YO[4 * q + 2] * eat) * silu_fast(z2), v3 = (yd.w + YO[4 * q + 3] * eat) * silu_fast(z3);
;                 y[tb][pb][4 * q] = v0; y[tb][pb][4 * q + 1] = v1; y[tb][pb][4 * q + 2] = v2; y[tb][pb][4 * q + 3] = v3; ssq += v0 * v0 + v1 * v1 + v2 * v2 + v3 * v3; }
;     ...
;             for (int q = 0; q < 4; ++q) { const int p0 = wave * 64 + 32 * pb + 8 * q + 4 * hh; const float4 gg = *(const float4*)(gn + p0);
	v_lshlrev_b32_e32 v218, 16, v96
	v_and_b32_e32 v219, 0xffff0000, v96
	v_lshlrev_b32_e32 v220, 16, v97
	v_and_b32_e32 v221, 0xffff0000, v97
	v_fma_f32 v124, v193, v14, v86
	v_mul_f32_e32 v50, 0xbfb8aa3b, v218
	v_exp_f32_e32 v50, v50
	s_nop 0
	v_add_f32_e32 v50, 1.0, v50
	v_div_scale_f32 v51, s[8:9], v50, v50, v218
	v_rcp_f32_e32 v52, v51
	s_nop 0
	v_fma_f32 v53, -v51, v52, 1.0
	v_fmac_f32_e32 v52, v53, v52
	v_div_scale_f32 v53, vcc, v218, v50, v218
	v_mul_f32_e32 v66, v53, v52
	v_fma_f32 v122, -v51, v66, v53
	v_fmac_f32_e32 v66, v122, v52
	v_fma_f32 v51, -v51, v66, v53
	v_div_fmas_f32 v51, v51, v52, v66
	v_div_fixup_f32 v123, v51, v50, v218
	v_mul_f32_e32 v169, v124, v123
	v_fmac_f32_e32 v217, v169, v169
	v_fma_f32 v124, v193, v15, v87
	v_mul_f32_e32 v50, 0xbfb8aa3b, v219
	v_exp_f32_e32 v50, v50
	s_nop 0
	v_add_f32_e32 v50, 1.0, v50
	v_div_scale_f32 v51, s[8:9], v50, v50, v219
	v_rcp_f32_e32 v52, v51
	s_nop 0
	v_fma_f32 v53, -v51, v52, 1.0
	v_fmac_f32_e32 v52, v53, v52
	v_div_scale_f32 v53, vcc, v219, v50, v219
	v_mul_f32_e32 v66, v53, v52
	v_fma_f32 v122, -v51, v66, v53
	v_fmac_f32_e32 v66, v122, v52
	v_fma_f32 v51, -v51, v66, v53
	v_div_fmas_f32 v51, v51, v52, v66
	v_div_fixup_f32 v123, v51, v50, v219
	v_mul_f32_e32 v170, v124, v123
	v_fmac_f32_e32 v217, v170, v170
	v_fma_f32 v124, v193, v16, v88
	v_mul_f32_e32 v50, 0xbfb8aa3b, v220
	v_exp_f32_e32 v50, v50
	s_nop 0
	v_add_f32_e32 v50, 1.0, v50
	v_div_scale_f32 v51, s[8:9], v50, v50, v220
	v_rcp_f32_e32 v52, v51
	s_nop 0
	v_fma_f32 v53, -v51, v52, 1.0
	v_fmac_f32_e32 v52, v53, v52
	v_div_scale_f32 v53, vcc, v220, v50, v220
	v_mul_f32_e32 v66, v53, v52
	v_fma_f32 v122, -v51, v66, v53
	v_fmac_f32_e32 v66, v122, v52
	v_fma_f32 v51, -v51, v66, v53
	v_div_fmas_f32 v51, v51, v52, v66
	v_div_fixup_f32 v123, v51, v50, v220
	v_mul_f32_e32 v171, v124, v123
	v_fmac_f32_e32 v217, v171, v171
	v_fma_f32 v124, v193, v17, v89
	v_mul_f32_e32 v50, 0xbfb8aa3b, v221
	v_exp_f32_e32 v50, v50
	s_nop 0
	v_add_f32_e32 v50, 1.0, v50
	v_div_scale_f32 v51, s[8:9], v50, v50, v221
	v_rcp_f32_e32 v52, v51
	s_nop 0
	v_fma_f32 v53, -v51, v52, 1.0
	v_fmac_f32_e32 v52, v53, v52
	v_div_scale_f32 v53, vcc, v221, v50, v221
	v_mul_f32_e32 v66, v53, v52
	v_fma_f32 v122, -v51, v66, v53
	v_fmac_f32_e32 v66, v122, v52
	v_fma_f32 v51, -v51, v66, v53
	v_div_fmas_f32 v51, v51, v52, v66
	v_div_fixup_f32 v123, v51, v50, v221
	v_mul_f32_e32 v172, v124, v123
	v_fmac_f32_e32 v217, v172, v172
	s_waitcnt vmcnt(11)
	v_mfma_f32_32x32x16_bf16 v[2:17], v[18:21], v[34:37], 0
	s_waitcnt vmcnt(10)
	v_mfma_f32_32x32x16_bf16 v[2:17], v[22:25], v[38:41], v[2:17]
	s_waitcnt vmcnt(9)
	v_mfma_f32_32x32x16_bf16 v[2:17], v[26:29], v[42:45], v[2:17]
	s_waitcnt vmcnt(8)
	v_mfma_f32_32x32x16_bf16 v[2:17], v[30:33], v[46:49], v[2:17]
	s_nop 7
	global_load_dwordx4 v[18:21], v[226:227], off offset:0
	global_load_dwordx4 v[22:25], v[226:227], off offset:32
	global_load_dwordx4 v[26:29], v[226:227], off offset:64
	global_load_dwordx4 v[30:33], v[226:227], off offset:96
	global_load_dwordx4 v[34:37], v[226:227], off offset:128
	global_load_dwordx4 v[38:41], v[226:227], off offset:160
	global_load_dwordx4 v[42:45], v[226:227], off offset:192
	global_load_dwordx4 v[46:49], v[226:227], off offset:224
	s_nop 15
	s_waitcnt vmcnt(11)
	v_lshlrev_b32_e32 v218, 16, v114
	v_and_b32_e32 v219, 0xffff0000, v114
	v_lshlrev_b32_e32 v220, 16, v115
	v_and_b32_e32 v221, 0xffff0000, v115
	v_fma_f32 v124, v193, v2, v98
	v_mul_f32_e32 v50, 0xbfb8aa3b, v218
	v_exp_f32_e32 v50, v50
	s_nop 0
	v_add_f32_e32 v50, 1.0, v50
	v_div_scale_f32 v51, s[8:9], v50, v50, v218
	v_rcp_f32_e32 v52, v51
	s_nop 0
	v_fma_f32 v53, -v51, v52, 1.0
	v_fmac_f32_e32 v52, v53, v52
	v_div_scale_f32 v53, vcc, v218, v50, v218
	v_mul_f32_e32 v66, v53, v52
	v_fma_f32 v122, -v51, v66, v53
	v_fmac_f32_e32 v66, v122, v52
	v_fma_f32 v51, -v51, v66, v53
	v_div_fmas_f32 v51, v51, v52, v66
	v_div_fixup_f32 v123, v51, v50, v218
	v_mul_f32_e32 v173, v124, v123
	v_fmac_f32_e32 v217, v173, v173
	v_fma_f32 v124, v193, v3, v99
	v_mul_f32_e32 v50, 0xbfb8aa3b, v219
	v_exp_f32_e32 v50, v50
	s_nop 0
	v_add_f32_e32 v50, 1.0, v50
	v_div_scale_f32 v51, s[8:9], v50, v50, v219
	v_rcp_f32_e32 v52, v51
	s_nop 0
	v_fma_f32 v53, -v51, v52, 1.0
	v_fmac_f32_e32 v52, v53, v52
	v_div_scale_f32 v53, vcc, v219, v50, v219
	v_mul_f32_e32 v66, v53, v52
	v_fma_f32 v122, -v51, v66, v53
	v_fmac_f32_e32 v66, v122, v52
	v_fma_f32 v51, -v51, v66, v53
	v_div_fmas_f32 v51, v51, v52, v66
	v_div_fixup_f32 v123, v51, v50, v219
	v_mul_f32_e32 v174, v124, v123
	v_fmac_f32_e32 v217, v174, v174
	v_fma_f32 v124, v193, v4, v100
	v_mul_f32_e32 v50, 0xbfb8aa3b, v220
	v_exp_f32_e32 v50, v50
	s_nop 0
	v_add_f32_e32 v50, 1.0, v50
	v_div_scale_f32 v51, s[8:9], v50, v50, v220
	v_rcp_f32_e32 v52, v51
	s_nop 0
	v_fma_f32 v53, -v51, v52, 1.0
	v_fmac_f32_e32 v52, v53, v52
	v_div_scale_f32 v53, vcc, v220, v50, v220
	v_mul_f32_e32 v66, v53, v52
	v_fma_f32 v122, -v51, v66, v53
	v_fmac_f32_e32 v66, v122, v52
	v_fma_f32 v51, -v51, v66, v53
	v_div_fmas_f32 v51, v51, v52, v66
	v_div_fixup_f32 v123, v51, v50, v220
	v_mul_f32_e32 v175, v124, v123
	v_fmac_f32_e32 v217, v175, v175
	v_fma_f32 v124, v193, v5, v101
	v_mul_f32_e32 v50, 0xbfb8aa3b, v221
	v_exp_f32_e32 v50, v50
	s_nop 0
	v_add_f32_e32 v50, 1.0, v50
	v_div_scale_f32 v51, s[8:9], v50, v50, v221
	v_rcp_f32_e32 v52, v51
	s_nop 0
	v_fma_f32 v53, -v51, v52, 1.0
	v_fmac_f32_e32 v52, v53, v52
	v_div_scale_f32 v53, vcc, v221, v50, v221
	v_mul_f32_e32 v66, v53, v52
	v_fma_f32 v122, -v51, v66, v53
	v_fmac_f32_e32 v66, v122, v52
	v_fma_f32 v51, -v51, v66, v53
	v_div_fmas_f32 v51, v51, v52, v66
	v_div_fixup_f32 v123, v51, v50, v221
	v_mul_f32_e32 v180, v124, v123
	v_fmac_f32_e32 v217, v180, v180
	s_waitcnt vmcnt(10)
;     DEVI bf16_t* proj() const { return (bf16_t*)(ws + WS_PROJ); }
;     DEVI float* ydg() const { return (float*)(ws + WS_YZ); }
; DEVI float silu_fast(float x) { return x / (1.f + __expf(-x)); }
; DEVI void ssd_y_unit(const P& p, int l, int ci, LAS unsigned char* lds, int tid, int wave, int lane) {
;     ...
;             for (int q = 0; q < 4; ++q) { const int p0 = wave * 64 + 32 * pb + 8 * q + 4 * hh;
;                 const float4 yd = *(const float4*)(p.ydg() + r * 512 + p0); const uint2 zz = *(const uint2*)(p.proj() + r * NP + O_Z + p0);
;                 const float z0 = __uint_as_float(zz.x << 16), z1 = __uint_as_float(zz.x & 0xffff0000u), z2 = __uint_as_float(zz.y << 16), z3 = __uint_as_float(zz.y & 0xffff0000u);
;                 const float v0 = (yd.x + YO[4 * q] * eat) * silu_fast(z0), v1 = (yd.y + YO[4 * q + 1] * eat) * silu_fast(z1), v2 = (yd.z + YO[4 * q + 2] * eat) * silu_fast(z2), v3 = (yd.w + YO[4 * q + 3] * eat) * silu_fast(z3);
;                 y[tb][pb][4 * q] = v0; y[tb][pb][4 * q + 1] = v1; y[tb][pb][4 * q + 2] = v2; y[tb][pb][4 * q + 3] = v3; ssq += v0 * v0 + v1 * v1 + v2 * v2 + v3 * v3; }
	v_lshlrev_b32_e32 v218, 16, v116
	v_and_b32_e32 v219, 0xffff0000, v116
	v_lshlrev_b32_e32 v220, 16, v117
	v_and_b32_e32 v221, 0xffff0000, v117
	v_fma_f32 v124, v193, v6, v102
	v_mul_f32_e32 v50, 0xbfb8aa3b, v218
	v_exp_f32_e32 v50, v50
	s_nop 0
	v_add_f32_e32 v50, 1.0, v50
	v_div_scale_f32 v51, s[8:9], v50, v50, v218
	v_rcp_f32_e32 v52, v51
	s_nop 0
	v_fma_f32 v53, -v51, v52, 1.0
	v_fmac_f32_e32 v52, v53, v52
	v_div_scale_f32 v53, vcc, v218, v50, v218
	v_mul_f32_e32 v66, v53, v52
	v_fma_f32 v122, -v51, v66, v53
	v_fmac_f32_e32 v66, v122, v52
	v_fma_f32 v51, -v51, v66, v53
	v_div_fmas_f32 v51, v51, v52, v66
	v_div_fixup_f32 v123, v51, v50, v218
	v_mul_f32_e32 v181, v124, v123
	v_fmac_f32_e32 v217, v181, v181
	v_fma_f32 v124, v193, v7, v103
	v_mul_f32_e32 v50, 0xbfb8aa3b, v219
	v_exp_f32_e32 v50, v50
	s_nop 0
	v_add_f32_e32 v50, 1.0, v50
	v_div_scale_f32 v51, s[8:9], v50, v50, v219
	v_rcp_f32_e32 v52, v51
	s_nop 0
	v_fma_f32 v53, -v51, v52, 1.0
	v_fmac_f32_e32 v52, v53, v52
	v_div_scale_f32 v53, vcc, v219, v50, v219
	v_mul_f32_e32 v66, v53, v52
	v_fma_f32 v122, -v51, v66, v53
	v_fmac_f32_e32 v66, v122, v52
	v_fma_f32 v51, -v51, v66, v53
	v_div_fmas_f32 v51, v51, v52, v66
	v_div_fixup_f32 v123, v51, v50, v219
	v_mul_f32_e32 v182, v124, v123
	v_fmac_f32_e32 v217, v182, v182
	v_fma_f32 v124, v193, v8, v104
	v_mul_f32_e32 v50, 0xbfb8aa3b, v220
	v_exp_f32_e32 v50, v50
	s_nop 0
	v_add_f32_e32 v50, 1.0, v50
	v_div_scale_f32 v51, s[8:9], v50, v50, v220
	v_rcp_f32_e32 v52, v51
	s_nop 0
	v_fma_f32 v53, -v51, v52, 1.0
	v_fmac_f32_e32 v52, v53, v52
	v_div_scale_f32 v53, vcc, v220, v50, v220
	v_mul_f32_e32 v66, v53, v52
	v_fma_f32 v122, -v51, v66, v53
	v_fmac_f32_e32 v66, v122, v52
	v_fma_f32 v51, -v51, v66, v53
	v_div_fmas_f32 v51, v51, v52, v66
	v_div_fixup_f32 v123, v51, v50, v220
	v_mul_f32_e32 v183, v124, v123
	v_fmac_f32_e32 v217, v183, v183
	v_fma_f32 v124, v193, v9, v105
	v_mul_f32_e32 v50, 0xbfb8aa3b, v221
	v_exp_f32_e32 v50, v50
	s_nop 0
	v_add_f32_e32 v50, 1.0, v50
	v_div_scale_f32 v51, s[8:9], v50, v50, v221
	v_rcp_f32_e32 v52, v51
	s_nop 0
	v_fma_f32 v53, -v51, v52, 1.0
	v_fmac_f32_e32 v52, v53, v52
	v_div_scale_f32 v53, vcc, v221, v50, v221
	v_mul_f32_e32 v66, v53, v52
	v_fma_f32 v122, -v51, v66, v53
	v_fmac_f32_e32 v66, v122, v52
	v_fma_f32 v51, -v51, v66, v53
	v_div_fmas_f32 v51, v51, v52, v66
	v_div_fixup_f32 v123, v51, v50, v221
	v_mul_f32_e32 v184, v124, v123
	v_fmac_f32_e32 v217, v184, v184
	s_waitcnt vmcnt(9)
	v_lshlrev_b32_e32 v218, 16, v118
	v_and_b32_e32 v219, 0xffff0000, v118
	v_lshlrev_b32_e32 v220, 16, v119
	v_and_b32_e32 v221, 0xffff0000, v119
	v_fma_f32 v124, v193, v10, v106
	v_mul_f32_e32 v50, 0xbfb8aa3b, v218
	v_exp_f32_e32 v50, v50
	s_nop 0
	v_add_f32_e32 v50, 1.0, v50
	v_div_scale_f32 v51, s[8:9], v50, v50, v218
	v_rcp_f32_e32 v52, v51
	s_nop 0
	v_fma_f32 v53, -v51, v52, 1.0
	v_fmac_f32_e32 v52, v53, v52
	v_div_scale_f32 v53, vcc, v218, v50, v218
	v_mul_f32_e32 v66, v53, v52
	v_fma_f32 v122, -v51, v66, v53
	v_fmac_f32_e32 v66, v122, v52
	v_fma_f32 v51, -v51, v66, v53
	v_div_fmas_f32 v51, v51, v52, v66
	v_div_fixup_f32 v123, v51, v50, v218
	v_mul_f32_e32 v185, v124, v123
	v_fmac_f32_e32 v217, v185, v185
	v_fma_f32 v124, v193, v11, v107
	v_mul_f32_e32 v50, 0xbfb8aa3b, v219
	v_exp_f32_e32 v50, v50
	s_nop 0
	v_add_f32_e32 v50, 1.0, v50
	v_div_scale_f32 v51, s[8:9], v50, v50, v219
	v_rcp_f32_e32 v52, v51
	s_nop 0
	v_fma_f32 v53, -v51, v52, 1.0
	v_fmac_f32_e32 v52, v53, v52
	v_div_scale_f32 v53, vcc, v219, v50, v219
	v_mul_f32_e32 v66, v53, v52
	v_fma_f32 v122, -v51, v66, v53
	v_fmac_f32_e32 v66, v122, v52
	v_fma_f32 v51, -v51, v66, v53
	v_div_fmas_f32 v51, v51, v52, v66
	v_div_fixup_f32 v123, v51, v50, v219
	v_mul_f32_e32 v186, v124, v123
	v_fmac_f32_e32 v217, v186, v186
	v_fma_f32 v124, v193, v12, v108
	v_mul_f32_e32 v50, 0xbfb8aa3b, v220
	v_exp_f32_e32 v50, v50
	s_nop 0
	v_add_f32_e32 v50, 1.0, v50
	v_div_scale_f32 v51, s[8:9], v50, v50, v220
	v_rcp_f32_e32 v52, v51
	s_nop 0
	v_fma_f32 v53, -v51, v52, 1.0
	v_fmac_f32_e32 v52, v53, v52
	v_div_scale_f32 v53, vcc, v220, v50, v220
	v_mul_f32_e32 v66, v53, v52
	v_fma_f32 v122, -v51, v66, v53
	v_fmac_f32_e32 v66, v122, v52
	v_fma_f32 v51, -v51, v66, v53
	v_div_fmas_f32 v51, v51, v52, v66
	v_div_fixup_f32 v123, v51, v50, v220
	v_mul_f32_e32 v187, v124, v123
	v_fmac_f32_e32 v217, v187, v187
	v_fma_f32 v124, v193, v13, v109
	v_mul_f32_e32 v50, 0xbfb8aa3b, v221
	v_exp_f32_e32 v50, v50
	s_nop 0
	v_add_f32_e32 v50, 1.0, v50
	v_div_scale_f32 v51, s[8:9], v50, v50, v221
	v_rcp_f32_e32 v52, v51
	s_nop 0
	v_fma_f32 v53, -v51, v52, 1.0
	v_fmac_f32_e32 v52, v53, v52
	v_div_scale_f32 v53, vcc, v221, v50, v221
	v_mul_f32_e32 v66, v53, v52
	v_fma_f32 v122, -v51, v66, v53
	v_fmac_f32_e32 v66, v122, v52
	v_fma_f32 v51, -v51, v66, v53
	v_div_fmas_f32 v51, v51, v52, v66
	v_div_fixup_f32 v123, v51, v50, v221
	v_mul_f32_e32 v188, v124, v123
	v_fmac_f32_e32 v217, v188, v188
	s_waitcnt vmcnt(8)
;     DEVI float* rstd() const { return (float*)(ws + WS_RSTD); }
; DEVI cfp_t inp(int i) { const __attribute__((address_space(4))) cfp_t* k = (const __attribute__((address_space(4))) cfp_t*)__builtin_amdgcn_kernarg_segment_ptr(); typedef const __attribute__((address_space(1))) float* gcfp_t; const gcfp_t r = *(const volatile __attribute__((address_space(4))) gcfp_t*)(k + i); return (cfp_t)r; }
; DEVI unsigned pk2bf(float lo, float hi) { unsigned r; asm volatile("v_cvt_pk_bf16_f32 %0, %1, %2" : "=v"(r) : "v"(lo), "v"(hi)); return r; }
; DEVI void ssd_y_unit(const P& p, int l, int ci, LAS unsigned char* lds, int tid, int wave, int lane) {
;     ...
;                 y[tb][pb][4 * q] = v0; y[tb][pb][4 * q + 1] = v1; y[tb][pb][4 * q + 2] = v2; y[tb][pb][4 * q + 3] = v3; ssq += v0 * v0 + v1 * v1 + v2 * v2 + v3 * v3; }
;         }
;         ssq += __shfl_xor(ssq, 32);
;         if (hh == 0) part[wave * 64 + 32 * tb + c32] = ssq;
;     }
;     __syncthreads();
;     const float* gn = inp(19) + (size_t)l * 512;
; #pragma unroll
;     for (int tb = 0; tb < 2; ++tb) {
;         const int t = 32 * tb + c32; float tot = 0.f;
; #pragma unroll
;         for (int w = 0; w < 8; ++w) tot += part[w * 64 + t];
;         const float rstd = rsqrtf(tot * (1.f / 512) + EPS); const size_t r = (size_t)r0 + t;
; #pragma unroll
;         for (int pb = 0; pb < 2; ++pb)
; #pragma unroll
;             for (int q = 0; q < 4; ++q) { const int p0 = wave * 64 + 32 * pb + 8 * q + 4 * hh; const float4 gg = *(const float4*)(gn + p0);
;                 uint2 o; o.x = pk2bf(y[tb][pb][4 * q] * rstd * gg.x, y[tb][pb][4 * q + 1] * rstd * gg.y); o.y = pk2bf(y[tb][pb][4 * q + 2] * rstd * gg.z, y[tb][pb][4 * q + 3] * rstd * gg.w);
	v_lshlrev_b32_e32 v218, 16, v120
	v_and_b32_e32 v219, 0xffff0000, v120
	v_lshlrev_b32_e32 v220, 16, v121
	v_and_b32_e32 v221, 0xffff0000, v121
	v_fma_f32 v124, v193, v14, v110
	v_mul_f32_e32 v50, 0xbfb8aa3b, v218
	v_exp_f32_e32 v50, v50
	s_nop 0
	v_add_f32_e32 v50, 1.0, v50
	v_div_scale_f32 v51, s[8:9], v50, v50, v218
	v_rcp_f32_e32 v52, v51
	s_nop 0
	v_fma_f32 v53, -v51, v52, 1.0
	v_fmac_f32_e32 v52, v53, v52
	v_div_scale_f32 v53, vcc, v218, v50, v218
	v_mul_f32_e32 v66, v53, v52
	v_fma_f32 v122, -v51, v66, v53
	v_fmac_f32_e32 v66, v122, v52
	v_fma_f32 v51, -v51, v66, v53
	v_div_fmas_f32 v51, v51, v52, v66
	v_div_fixup_f32 v123, v51, v50, v218
	v_mul_f32_e32 v189, v124, v123
	v_fmac_f32_e32 v217, v189, v189
	v_fma_f32 v124, v193, v15, v111
	v_mul_f32_e32 v50, 0xbfb8aa3b, v219
	v_exp_f32_e32 v50, v50
	s_nop 0
	v_add_f32_e32 v50, 1.0, v50
	v_div_scale_f32 v51, s[8:9], v50, v50, v219
	v_rcp_f32_e32 v52, v51
	s_nop 0
	v_fma_f32 v53, -v51, v52, 1.0
	v_fmac_f32_e32 v52, v53, v52
	v_div_scale_f32 v53, vcc, v219, v50, v219
	v_mul_f32_e32 v66, v53, v52
	v_fma_f32 v122, -v51, v66, v53
	v_fmac_f32_e32 v66, v122, v52
	v_fma_f32 v51, -v51, v66, v53
	v_div_fmas_f32 v51, v51, v52, v66
	v_div_fixup_f32 v123, v51, v50, v219
	v_mul_f32_e32 v190, v124, v123
	v_fmac_f32_e32 v217, v190, v190
	v_fma_f32 v124, v193, v16, v112
	v_mul_f32_e32 v50, 0xbfb8aa3b, v220
	v_exp_f32_e32 v50, v50
	s_nop 0
	v_add_f32_e32 v50, 1.0, v50
	v_div_scale_f32 v51, s[8:9], v50, v50, v220
	v_rcp_f32_e32 v52, v51
	s_nop 0
	v_fma_f32 v53, -v51, v52, 1.0
	v_fmac_f32_e32 v52, v53, v52
	v_div_scale_f32 v53, vcc, v220, v50, v220
	v_mul_f32_e32 v66, v53, v52
	v_fma_f32 v122, -v51, v66, v53
	v_fmac_f32_e32 v66, v122, v52
	v_fma_f32 v51, -v51, v66, v53
	v_div_fmas_f32 v51, v51, v52, v66
	v_div_fixup_f32 v123, v51, v50, v220
	v_mul_f32_e32 v191, v124, v123
	v_fmac_f32_e32 v217, v191, v191
	v_fma_f32 v124, v193, v17, v113
	v_mul_f32_e32 v50, 0xbfb8aa3b, v221
	v_exp_f32_e32 v50, v50
	s_nop 0
	v_add_f32_e32 v50, 1.0, v50
	v_div_scale_f32 v51, s[8:9], v50, v50, v221
	v_rcp_f32_e32 v52, v51
	s_nop 0
	v_fma_f32 v53, -v51, v52, 1.0
	v_fmac_f32_e32 v52, v53, v52
	v_div_scale_f32 v53, vcc, v221, v50, v221
	v_mul_f32_e32 v66, v53, v52
	v_fma_f32 v122, -v51, v66, v53
	v_fmac_f32_e32 v66, v122, v52
	v_fma_f32 v51, -v51, v66, v53
	v_div_fmas_f32 v51, v51, v52, v66
	v_div_fixup_f32 v123, v51, v50, v221
	v_mul_f32_e32 v192, v124, v123
	v_fmac_f32_e32 v217, v192, v192
	s_nop 1
	ds_bpermute_b32 v124, v208, v217
	s_waitcnt lgkmcnt(0)
	v_add_f32_e32 v217, v217, v124
	s_and_saveexec_b64 s[8:9], s[2:3]
	ds_write_b32 v1, v217 offset:128
	s_or_b64 exec, exec, s[8:9]
	s_waitcnt lgkmcnt(0)
	s_barrier
	ds_read2st64_b32 v[74:75], v55 offset1:1
	ds_read2st64_b32 v[76:77], v55 offset0:2 offset1:3
	ds_read2st64_b32 v[78:79], v55 offset0:4 offset1:5
	ds_read2st64_b32 v[80:81], v55 offset0:6 offset1:7
	v_mov_b32_e32 v233, 0
	v_or_b32_e32 v232, s11, v54
	v_lshlrev_b64 v[234:235], 11, v[232:233]
	v_lshl_add_u64 v[234:235], v[72:73], 0, v[234:235]
	s_waitcnt lgkmcnt(0)
	v_add_f32_e32 v74, 0, v74
	v_add_f32_e32 v74, v74, v75
	v_add_f32_e32 v74, v74, v76
	v_add_f32_e32 v74, v74, v77
	v_add_f32_e32 v74, v74, v78
	v_add_f32_e32 v74, v74, v79
	v_add_f32_e32 v74, v74, v80
	v_add_f32_e32 v74, v74, v81
	v_mov_b32_e32 v75, 0x3b000000
	v_fma_f32 v74, v74, v75, v211
	s_mov_b32 s7, 0x800000
	v_cmp_gt_f32_e32 vcc, s7, v74
	v_mul_f32_e32 v75, 0x4b800000, v74
	s_nop 1
	v_cndmask_b32_e32 v74, v74, v75, vcc
	v_rsq_f32_e32 v74, v74
	s_nop 0
	v_mul_f32_e32 v75, 0x45800000, v74
	v_cndmask_b32_e32 v82, v74, v75, vcc
	s_waitcnt vmcnt(7)
	v_mul_f32_e32 v83, v125, v82
	v_mul_f32_e32 v83, v18, v83
	v_mul_f32_e32 v84, v126, v82
	v_mul_f32_e32 v84, v19, v84
	v_mul_f32_e32 v85, v127, v82
	v_mul_f32_e32 v85, v20, v85
	v_mul_f32_e32 v86, v128, v82
	v_mul_f32_e32 v86, v21, v86
	v_cvt_pk_bf16_f32 v88, v83, v84
	v_cvt_pk_bf16_f32 v89, v85, v86
	global_store_dwordx2 v[234:235], v[88:89], off offset:0
	s_waitcnt vmcnt(6)
	v_mul_f32_e32 v83, v129, v82
	v_mul_f32_e32 v83, v22, v83
	v_mul_f32_e32 v84, v130, v82
	v_mul_f32_e32 v84, v23, v84
	v_mul_f32_e32 v85, v131, v82
	v_mul_f32_e32 v85, v24, v85
	v_mul_f32_e32 v86, v132, v82
	v_mul_f32_e32 v86, v25, v86
	v_cvt_pk_bf16_f32 v88, v83, v84
	v_cvt_pk_bf16_f32 v89, v85, v86
	global_store_dwordx2 v[234:235], v[88:89], off offset:16
	s_waitcnt vmcnt(5)
	v_mul_f32_e32 v83, v133, v82
	v_mul_f32_e32 v83, v26, v83
	v_mul_f32_e32 v84, v134, v82
	v_mul_f32_e32 v84, v27, v84
	v_mul_f32_e32 v85, v135, v82
	v_mul_f32_e32 v85, v28, v85
	v_mul_f32_e32 v86, v136, v82
	v_mul_f32_e32 v86, v29, v86
	v_cvt_pk_bf16_f32 v88, v83, v84
	v_cvt_pk_bf16_f32 v89, v85, v86
	global_store_dwordx2 v[234:235], v[88:89], off offset:32
	s_waitcnt vmcnt(4)
	v_mul_f32_e32 v83, v137, v82
	v_mul_f32_e32 v83, v30, v83
	v_mul_f32_e32 v84, v138, v82
	v_mul_f32_e32 v84, v31, v84
	v_mul_f32_e32 v85, v139, v82
	v_mul_f32_e32 v85, v32, v85
	v_mul_f32_e32 v86, v140, v82
	v_mul_f32_e32 v86, v33, v86
	v_cvt_pk_bf16_f32 v88, v83, v84
	v_cvt_pk_bf16_f32 v89, v85, v86
	global_store_dwordx2 v[234:235], v[88:89], off offset:48
	s_waitcnt vmcnt(3)
;     DEVI float* rstd() const { return (float*)(ws + WS_RSTD); }
;     DEVI bf16_t* mix() const { return (bf16_t*)(ws + WS_MIX); }
; DEVI unsigned pk2bf(float lo, float hi) { unsigned r; asm volatile("v_cvt_pk_bf16_f32 %0, %1, %2" : "=v"(r) : "v"(lo), "v"(hi)); return r; }
; DEVI void ssd_y_unit(const P& p, int l, int ci, LAS unsigned char* lds, int tid, int wave, int lane) {
;     ...
;     for (int tb = 0; tb < 2; ++tb) {
;         const int t = 32 * tb + c32; float tot = 0.f;
; #pragma unroll
;         for (int w = 0; w < 8; ++w) tot += part[w * 64 + t];
;         const float rstd = rsqrtf(tot * (1.f / 512) + EPS); const size_t r = (size_t)r0 + t;
; #pragma unroll
;         for (int pb = 0; pb < 2; ++pb)
; #pragma unroll
;             for (int q = 0; q < 4; ++q) { const int p0 = wave * 64 + 32 * pb + 8 * q + 4 * hh; const float4 gg = *(const float4*)(gn + p0);
;                 uint2 o; o.x = pk2bf(y[tb][pb][4 * q] * rstd * gg.x, y[tb][pb][4 * q + 1] * rstd * gg.y); o.y = pk2bf(y[tb][pb][4 * q + 2] * rstd * gg.z, y[tb][pb][4 * q + 3] * rstd * gg.w);
;                 *(uint2*)(p.mix() + r * D + p0) = o; }
;     }
;     __syncthreads();
	v_mul_f32_e32 v83, v141, v82
	v_mul_f32_e32 v83, v34, v83
	v_mul_f32_e32 v84, v142, v82
	v_mul_f32_e32 v84, v35, v84
	v_mul_f32_e32 v85, v143, v82
	v_mul_f32_e32 v85, v36, v85
	v_mul_f32_e32 v86, v144, v82
	v_mul_f32_e32 v86, v37, v86
	v_cvt_pk_bf16_f32 v88, v83, v84
	v_cvt_pk_bf16_f32 v89, v85, v86
	global_store_dwordx2 v[234:235], v[88:89], off offset:64
	s_waitcnt vmcnt(2)
	v_mul_f32_e32 v83, v145, v82
	v_mul_f32_e32 v83, v38, v83
	v_mul_f32_e32 v84, v146, v82
	v_mul_f32_e32 v84, v39, v84
	v_mul_f32_e32 v85, v147, v82
	v_mul_f32_e32 v85, v40, v85
	v_mul_f32_e32 v86, v148, v82
	v_mul_f32_e32 v86, v41, v86
	v_cvt_pk_bf16_f32 v88, v83, v84
	v_cvt_pk_bf16_f32 v89, v85, v86
	global_store_dwordx2 v[234:235], v[88:89], off offset:80
	s_waitcnt vmcnt(1)
	v_mul_f32_e32 v83, v149, v82
	v_mul_f32_e32 v83, v42, v83
	v_mul_f32_e32 v84, v150, v82
	v_mul_f32_e32 v84, v43, v84
	v_mul_f32_e32 v85, v151, v82
	v_mul_f32_e32 v85, v44, v85
	v_mul_f32_e32 v86, v152, v82
	v_mul_f32_e32 v86, v45, v86
	v_cvt_pk_bf16_f32 v88, v83, v84
	v_cvt_pk_bf16_f32 v89, v85, v86
	global_store_dwordx2 v[234:235], v[88:89], off offset:96
	s_waitcnt vmcnt(0)
	v_mul_f32_e32 v83, v153, v82
	v_mul_f32_e32 v83, v46, v83
	v_mul_f32_e32 v84, v154, v82
	v_mul_f32_e32 v84, v47, v84
	v_mul_f32_e32 v85, v155, v82
	v_mul_f32_e32 v85, v48, v85
	v_mul_f32_e32 v86, v156, v82
	v_mul_f32_e32 v86, v49, v86
	v_cvt_pk_bf16_f32 v88, v83, v84
	v_cvt_pk_bf16_f32 v89, v85, v86
	global_store_dwordx2 v[234:235], v[88:89], off offset:112
	ds_read2st64_b32 v[74:75], v65 offset1:1
	ds_read2st64_b32 v[76:77], v65 offset0:2 offset1:3
	ds_read2st64_b32 v[78:79], v65 offset0:4 offset1:5
	ds_read2st64_b32 v[80:81], v65 offset0:6 offset1:7
	v_mov_b32_e32 v233, 0
	v_or_b32_e32 v232, s11, v64
	v_lshlrev_b64 v[234:235], 11, v[232:233]
	v_lshl_add_u64 v[234:235], v[72:73], 0, v[234:235]
	s_waitcnt lgkmcnt(0)
	v_add_f32_e32 v74, 0, v74
	v_add_f32_e32 v74, v74, v75
	v_add_f32_e32 v74, v74, v76
	v_add_f32_e32 v74, v74, v77
	v_add_f32_e32 v74, v74, v78
	v_add_f32_e32 v74, v74, v79
	v_add_f32_e32 v74, v74, v80
	v_add_f32_e32 v74, v74, v81
	v_mov_b32_e32 v75, 0x3b000000
	v_fma_f32 v74, v74, v75, v211
	s_mov_b32 s7, 0x800000
	v_cmp_gt_f32_e32 vcc, s7, v74
	v_mul_f32_e32 v75, 0x4b800000, v74
	s_nop 1
	v_cndmask_b32_e32 v74, v74, v75, vcc
	v_rsq_f32_e32 v74, v74
	s_nop 0
	v_mul_f32_e32 v75, 0x45800000, v74
	v_cndmask_b32_e32 v82, v74, v75, vcc
	v_mul_f32_e32 v83, v157, v82
	v_mul_f32_e32 v83, v18, v83
	v_mul_f32_e32 v84, v158, v82
	v_mul_f32_e32 v84, v19, v84
	v_mul_f32_e32 v85, v159, v82
	v_mul_f32_e32 v85, v20, v85
	v_mul_f32_e32 v86, v160, v82
	v_mul_f32_e32 v86, v21, v86
	v_cvt_pk_bf16_f32 v88, v83, v84
	v_cvt_pk_bf16_f32 v89, v85, v86
	global_store_dwordx2 v[234:235], v[88:89], off offset:0
	v_mul_f32_e32 v83, v161, v82
	v_mul_f32_e32 v83, v22, v83
	v_mul_f32_e32 v84, v162, v82
	v_mul_f32_e32 v84, v23, v84
	v_mul_f32_e32 v85, v163, v82
	v_mul_f32_e32 v85, v24, v85
	v_mul_f32_e32 v86, v164, v82
	v_mul_f32_e32 v86, v25, v86
	v_cvt_pk_bf16_f32 v88, v83, v84
	v_cvt_pk_bf16_f32 v89, v85, v86
	global_store_dwordx2 v[234:235], v[88:89], off offset:16
	v_mul_f32_e32 v83, v165, v82
	v_mul_f32_e32 v83, v26, v83
	v_mul_f32_e32 v84, v166, v82
	v_mul_f32_e32 v84, v27, v84
	v_mul_f32_e32 v85, v167, v82
	v_mul_f32_e32 v85, v28, v85
	v_mul_f32_e32 v86, v168, v82
	v_mul_f32_e32 v86, v29, v86
	v_cvt_pk_bf16_f32 v88, v83, v84
	v_cvt_pk_bf16_f32 v89, v85, v86
	global_store_dwordx2 v[234:235], v[88:89], off offset:32
	v_mul_f32_e32 v83, v169, v82
	v_mul_f32_e32 v83, v30, v83
	v_mul_f32_e32 v84, v170, v82
	v_mul_f32_e32 v84, v31, v84
	v_mul_f32_e32 v85, v171, v82
	v_mul_f32_e32 v85, v32, v85
	v_mul_f32_e32 v86, v172, v82
	v_mul_f32_e32 v86, v33, v86
	v_cvt_pk_bf16_f32 v88, v83, v84
	v_cvt_pk_bf16_f32 v89, v85, v86
	global_store_dwordx2 v[234:235], v[88:89], off offset:48
	v_mul_f32_e32 v83, v173, v82
	v_mul_f32_e32 v83, v34, v83
	v_mul_f32_e32 v84, v174, v82
	v_mul_f32_e32 v84, v35, v84
	v_mul_f32_e32 v85, v175, v82
	v_mul_f32_e32 v85, v36, v85
	v_mul_f32_e32 v86, v180, v82
	v_mul_f32_e32 v86, v37, v86
	v_cvt_pk_bf16_f32 v88, v83, v84
	v_cvt_pk_bf16_f32 v89, v85, v86
	global_store_dwordx2 v[234:235], v[88:89], off offset:64
	v_mul_f32_e32 v83, v181, v82
	v_mul_f32_e32 v83, v38, v83
	v_mul_f32_e32 v84, v182, v82
	v_mul_f32_e32 v84, v39, v84
	v_mul_f32_e32 v85, v183, v82
	v_mul_f32_e32 v85, v40, v85
	v_mul_f32_e32 v86, v184, v82
	v_mul_f32_e32 v86, v41, v86
	v_cvt_pk_bf16_f32 v88, v83, v84
	v_cvt_pk_bf16_f32 v89, v85, v86
	global_store_dwordx2 v[234:235], v[88:89], off offset:80
	v_mul_f32_e32 v83, v185, v82
	v_mul_f32_e32 v83, v42, v83
	v_mul_f32_e32 v84, v186, v82
	v_mul_f32_e32 v84, v43, v84
	v_mul_f32_e32 v85, v187, v82
	v_mul_f32_e32 v85, v44, v85
	v_mul_f32_e32 v86, v188, v82
	v_mul_f32_e32 v86, v45, v86
	v_cvt_pk_bf16_f32 v88, v83, v84
	v_cvt_pk_bf16_f32 v89, v85, v86
	global_store_dwordx2 v[234:235], v[88:89], off offset:96
	v_mul_f32_e32 v83, v189, v82
	v_mul_f32_e32 v83, v46, v83
	v_mul_f32_e32 v84, v190, v82
	v_mul_f32_e32 v84, v47, v84
	v_mul_f32_e32 v85, v191, v82
	v_mul_f32_e32 v85, v48, v85
	v_mul_f32_e32 v86, v192, v82
	v_mul_f32_e32 v86, v49, v86
	v_cvt_pk_bf16_f32 v88, v83, v84
	v_cvt_pk_bf16_f32 v89, v85, v86
	global_store_dwordx2 v[234:235], v[88:89], off offset:112
	s_add_i32 s10, s10, s80
	s_add_i32 s6, s6, s34
	s_add_i32 s11, s11, s83
	s_barrier
	s_cmpk_gt_i32 s10, 0xff
	s_cbranch_scc0 .LBB0_700
